# GLA prompt: hoist next-chunk and gate loads to chunk top (staging regs); sample attn: D16/D4 row dedup + 2x unrolled loads
# speedup vs baseline: 1.0057x; 1.0057x over previous
; #define LAS __attribute__((address_space(3)))
; __device__ __forceinline__ bf16x8 pk8(f32x4 a, f32x4 b) { return __builtin_bit_cast(bf16x8, pack8(a, b)); }
; __device__ __forceinline__ void gla_prompt_item(Frame& F, int b, int h) {
;     ...
;                 const int t = 16 * tb + i16, s0 = 16 * sb + 4 * g;
; #pragma unroll
;                 for (int r = 0; r < 4; ++r) if (s0 + r > t) c4[r] = 0.f;
;                 v2u pk; pk.x = pk2(c4[0], c4[1]); pk.y = pk2(c4[2], c4[3]);
;                 *(LAS v2u*)(L + G_P + t * G_RP + s0 * 2) = pk;
;             }
;         }
;         LBAR();
;         if (var != 1) {
;             bf16x8 vf[2];
; #pragma unroll
;             for (int sp = 0; sp < 2; ++sp) { const LAS unsigned char* vp = L + G_V + (32 * sp + 8 * g + (i16 >> 2)) * G_VP + (16 * w + 4 * (i16 & 3)) * 2; vf[sp] = cat8(tr16(vp), tr16(vp + 4 * G_VP)); }
;             bf16x8 pa[4][2], qa[4][2];
; #pragma unroll
;             for (int tb = 0; tb < 4; ++tb)
; #pragma unroll
;                 for (int sp = 0; sp < 2; ++sp) {
;                     if (!(sp == 1 && tb < 2)) pa[tb][sp] = *(const LAS bf16x8*)(L + G_P + (16 * tb + i16) * G_RP + (32 * sp + 8 * g) * 2);
;                     const v2u a0 = *(const LAS v2u*)(L + G_QT + (16 * tb + i16) * G_RP + (32 * sp + 4 * g) * 2);
;                     const v2u a1 = *(const LAS v2u*)(L + G_QT + (16 * tb + i16) * G_RP + (32 * sp + 16 + 4 * g) * 2);
;                     v4u aa; aa.x = a0.x; aa.y = a0.y; aa.z = a1.x; aa.w = a1.y; qa[tb][sp] = __builtin_bit_cast(bf16x8, aa);
;                 }
;             bf16x8 bs[2];
; #pragma unroll
;             for (int sp = 0; sp < 2; ++sp) bs[sp] = pk8(sacc[2 * sp], sacc[2 * sp + 1]);
;             __builtin_amdgcn_sched_barrier(0);
;             f32x4 oacc[4];
; #pragma unroll
;             for (int tb = 0; tb < 4; ++tb) oacc[tb] = MFMA16(qa[tb][0], bs[0], ((f32x4){0.f, 0.f, 0.f, 0.f}));
; #pragma unroll
;             for (int tb = 0; tb < 4; ++tb) oacc[tb] = MFMA16(qa[tb][1], bs[1], oacc[tb]);
; #pragma unroll
;             for (int tb = 0; tb < 4; ++tb) oacc[tb] = MFMA16(pa[tb][0], vf[0], oacc[tb]);
; #pragma unroll
;             for (int tb = 2; tb < 4; ++tb) oacc[tb] = MFMA16(pa[tb][1], vf[1], oacc[tb]);
;             __builtin_amdgcn_sched_barrier(0);
;             bf16x8 ka[4][2]; f32x4 dv[4];
; #pragma unroll
;             for (int kb = 0; kb < 4; ++kb) {
; #pragma unroll
.LBB0_594:
	s_nop 6
	v_cndmask_b32_e64 v54, v50, 0, s[46:47]
	v_cndmask_b32_e64 v51, 0, v51, s[48:49]
	v_cndmask_b32_e64 v50, v54, v50, s[48:49]
	v_cndmask_b32_e64 v52, v52, 0, s[50:51]
	v_cndmask_b32_e64 v53, v53, 0, s[52:53]
	v_cvt_pk_bf16_f32 v50, v50, v51
	v_cvt_pk_bf16_f32 v51, v52, v53
	ds_write_b64 v118, v[50:51] offset:36864
	v_add_u32_e32 v164, v116, v119
	s_waitcnt lgkmcnt(0)
	s_barrier
	v_add_u32_e32 v144, 0x800, v164
	v_add_u32_e32 v160, 0x1000, v164
	v_add_u32_e32 v172, 0x1800, v164
	ds_read_b64_tr_b16 v[54:55], v135 offset:18432
	ds_read_b64_tr_b16 v[56:57], v135 offset:19584
	ds_read_b64_tr_b16 v[50:51], v135 offset:27648
	ds_read_b64_tr_b16 v[52:53], v135 offset:28800
	v_add_u32_e32 v139, v117, v119
	ds_read2_b64 v[58:61], v164 offset1:4
	ds_read2_b64 v[62:65], v164 offset0:8 offset1:12
	ds_read_b128 v[66:69], v139 offset:36864
	ds_read_b128 v[70:73], v139 offset:39168
	ds_read2_b64 v[140:143], v144 offset0:32 offset1:36
	ds_read2_b64 v[144:147], v144 offset0:40 offset1:44
	ds_read2_b64 v[148:151], v160 offset0:64 offset1:68
	ds_read_b128 v[152:155], v139 offset:41472
	ds_read_b128 v[156:159], v139 offset:41536
	ds_read2_b64 v[160:163], v160 offset0:72 offset1:76
	ds_read2_b64 v[164:167], v172 offset0:96 offset1:100
	ds_read_b128 v[168:171], v139 offset:43776
	ds_read_b128 v[176:179], v139 offset:43840
	ds_read2_b64 v[180:183], v172 offset0:104 offset1:108
	v_cvt_pk_bf16_f32 v184, v38, v39
	v_cvt_pk_bf16_f32 v185, v40, v41
	v_cvt_pk_bf16_f32 v186, v34, v35
	v_cvt_pk_bf16_f32 v187, v36, v37
	v_cvt_pk_bf16_f32 v188, v30, v31
	v_cvt_pk_bf16_f32 v189, v32, v33
	v_cvt_pk_bf16_f32 v190, v26, v27
	v_cvt_pk_bf16_f32 v191, v28, v29
	s_waitcnt lgkmcnt(13)
	v_mfma_f32_16x16x32_bf16 v[58:61], v[58:61], v[184:187], 0
	s_waitcnt lgkmcnt(9)
	v_mfma_f32_16x16x32_bf16 v[140:143], v[140:143], v[184:187], 0
	s_waitcnt lgkmcnt(7)
	v_mfma_f32_16x16x32_bf16 v[148:151], v[148:151], v[184:187], 0
	s_waitcnt lgkmcnt(3)
	v_mfma_f32_16x16x32_bf16 v[164:167], v[164:167], v[184:187], 0
	v_mfma_f32_16x16x32_bf16 v[58:61], v[62:65], v[188:191], v[58:61]
	v_mfma_f32_16x16x32_bf16 v[62:65], v[144:147], v[188:191], v[140:143]
	v_mfma_f32_16x16x32_bf16 v[140:143], v[160:163], v[188:191], v[148:151]
	s_waitcnt lgkmcnt(0)
	v_mfma_f32_16x16x32_bf16 v[144:147], v[180:183], v[188:191], v[164:167]
	v_mfma_f32_16x16x32_bf16 v[58:61], v[66:69], v[54:57], v[58:61]
	v_mfma_f32_16x16x32_bf16 v[62:65], v[70:73], v[54:57], v[62:65]
	v_mfma_f32_16x16x32_bf16 v[66:69], v[152:155], v[54:57], v[140:143]
	v_mfma_f32_16x16x32_bf16 v[70:73], v[168:171], v[54:57], v[144:147]
	v_mfma_f32_16x16x32_bf16 v[66:69], v[156:159], v[50:53], v[66:69]
	v_mfma_f32_16x16x32_bf16 v[70:73], v[176:179], v[50:53], v[70:73]
	ds_read_b128 v[140:143], v120
	s_nop 0
	ds_read_b128 v[144:147], v120 offset:64
	ds_read_b64_tr_b16 v[148:149], v136 offset:9216
	ds_read_b64_tr_b16 v[152:153], v136 offset:9248
	ds_read_b64_tr_b16 v[156:157], v136 offset:9280
	ds_read_b64_tr_b16 v[160:161], v136 offset:9312
	ds_read_b64_tr_b16 v[150:151], v136 offset:9792
	ds_read_b64_tr_b16 v[154:155], v136 offset:9824
	ds_read_b64_tr_b16 v[158:159], v136 offset:9856
	ds_read_b64_tr_b16 v[162:163], v136 offset:9888
	ds_read_b64_tr_b16 v[164:165], v136 offset:13824
	ds_read_b64_tr_b16 v[168:169], v136 offset:13856
	ds_read_b64_tr_b16 v[176:177], v136 offset:13888
	ds_read_b64_tr_b16 v[180:181], v136 offset:13920
	ds_read_b64_tr_b16 v[166:167], v136 offset:14400
	ds_read_b64_tr_b16 v[170:171], v136 offset:14432
	ds_read_b64_tr_b16 v[178:179], v136 offset:14464
	ds_read_b64_tr_b16 v[182:183], v136 offset:14496
	ds_read_b128 v[184:187], v120 offset:128
	ds_read_b128 v[188:191], v120 offset:192
	ds_write_b32 v137, v58 offset:46080
	v_add_u32_e32 v58, 0xb400, v138
	ds_write2_b32 v58, v59, v60 offset1:132
	ds_write_b32 v138, v61 offset:47136
	v_add_u32_e32 v58, 0xd200, v138
	ds_write2_b32 v58, v62, v63 offset0:60 offset1:192
	ds_write2_b32 v123, v64, v65 offset1:132
	ds_write2_b32 v124, v66, v67 offset0:56 offset1:188
	ds_write_b32 v122, v68 offset:54528
	ds_write_b32 v125, v69 offset:46080
	ds_write2_b32 v126, v70, v71 offset0:52 offset1:184
	ds_write2_b32 v127, v72, v73 offset0:60 offset1:192
	s_waitcnt lgkmcnt(0)
	s_barrier
	ds_read_b128 v[58:61], v128 offset:46080
	ds_read_b128 v[62:65], v128 offset:46096
	ds_read_b128 v[66:69], v128 offset:46112
	ds_read_b128 v[70:73], v128 offset:46128
	s_waitcnt lgkmcnt(14)
	v_mfma_f32_16x16x32_bf16 v[38:41], v[148:151], v[54:57], v[38:41]
	s_add_i32 s1, s1, -1
	s_waitcnt lgkmcnt(3)
	v_pk_mul_f32 v[148:149], v[60:61], v[60:61]
	v_pk_mul_f32 v[150:151], v[58:59], v[58:59]
	v_mfma_f32_16x16x32_bf16 v[34:37], v[152:155], v[54:57], v[34:37]
	v_pk_mov_b32 v[152:153], v[150:151], v[148:149] op_sel:[1,0]
	v_mov_b32_e32 v151, v149
	s_waitcnt lgkmcnt(2)
	v_pk_mul_f32 v[148:149], v[62:63], v[62:63]
	v_mfma_f32_16x16x32_bf16 v[30:33], v[156:159], v[54:57], v[30:33]
	s_waitcnt lgkmcnt(0)
; #define LAS __attribute__((address_space(3)))
; #define LBAR() do { asm volatile("s_waitcnt lgkmcnt(0)" ::: "memory"); __builtin_amdgcn_s_barrier(); asm volatile("" ::: "memory"); } while (0)
; __device__ __forceinline__ v4u pack8(const f32x4 a, const f32x4 b) { v4u w; w.x = pk2(a[0], a[1]); w.y = pk2(a[2], a[3]); w.z = pk2(b[0], b[1]); w.w = pk2(b[2], b[3]); return w; }
; #define MFMA16(a, b, c) __builtin_amdgcn_mfma_f32_16x16x32_bf16((a), (b), (c), 0, 0, 0)
; __device__ __forceinline__ void gla_prompt_item(Frame& F, int b, int h) {
;     ...
;             for (int kb = 0; kb < 4; ++kb) sacc[kb] = MFMA16(ka[kb][0], vf[0], sacc[kb]);
; #pragma unroll
;             for (int kb = 0; kb < 4; ++kb) sacc[kb] = MFMA16(ka[kb][1], vf[1], sacc[kb]);
; #pragma unroll
;             for (int kb = 0; kb < 4; ++kb) sacc[kb] = sacc[kb] * dv[kb];
;         }
;         LBAR();
;         {
;             f32x4 o4[4]; float ss = 0.f;
; #pragma unroll
;             for (int q = 0; q < 4; ++q) { o4[q] = *(const LAS f32x4*)(L + G_O + et * G_OP + (16 * evc + 4 * q) * 4); ss += (o4[q][0] * o4[q][0] + o4[q][1] * o4[q][1]) + (o4[q][2] * o4[q][2] + o4[q][3] * o4[q][3]); }
;             ss += __shfl_xor(ss, 1); ss += __shfl_xor(ss, 2); ss += __shfl_xor(ss, 4);
;             const float rn = __builtin_amdgcn_rsqf(ss * (1.0f / 128.0f) + EPS);
; #pragma unroll
;             for (int i = 0; i < 2; ++i) {
;                 const f32x4 ga = {bflo(gg[i].x), bfhi(gg[i].x), bflo(gg[i].y), bfhi(gg[i].y)}, gb = {bflo(gg[i].z), bfhi(gg[i].z), bflo(gg[i].w), bfhi(gg[i].w)};
;                 const f32x4 ra = o4[2 * i] * rn * gw4[2 * i] * ga, rb = o4[2 * i + 1] * rn * gw4[2 * i + 1] * gb;
;                 outp[i] = pack8(ra, rb);
;             }
;         }
	v_mul_f32_e32 v139, v70, v70
	v_lshl_add_u64 v[86:87], v[86:87], 0, s[76:77]
	v_lshl_add_u64 v[88:89], v[88:89], 0, s[76:77]
	v_mfma_f32_16x16x32_bf16 v[26:29], v[160:163], v[54:57], v[26:29]
	v_mul_f32_e64 v56, v64, v64
	v_mul_f32_e64 v57, v65, v65
	v_pk_add_f32 v[54:55], v[152:153], v[150:151]
	v_pk_mov_b32 v[150:151], v[148:149], v[56:57] op_sel:[1,0]
	v_mov_b32_e32 v149, v57
	v_pk_add_f32 v[56:57], v[150:151], v[148:149]
	v_mul_f32_e32 v148, v71, v71
	v_pk_add_f32 v[54:55], v[54:55], v[54:55] op_sel:[0,1] op_sel_hi:[1,0]
	v_pk_add_f32 v[56:57], v[56:57], v[56:57] op_sel:[0,1] op_sel_hi:[1,0]
	v_mov_b32_e32 v55, v139
	v_mov_b32_e32 v57, v148
	v_pk_add_f32 v[54:55], v[54:55], v[56:57]
	v_mul_f32_e32 v56, v67, v67
	v_mul_f32_e32 v149, v72, v72
	v_pk_fma_f32 v[56:57], v[66:67], v[66:67], v[56:57] op_sel_hi:[1,1,0]
	v_mul_f32_e32 v148, v69, v69
	v_mul_f32_e32 v150, v73, v73
	v_mov_b32_e32 v57, v149
	v_pk_fma_f32 v[148:149], v[68:69], v[68:69], v[148:149] op_sel_hi:[1,1,0]
	v_mfma_f32_16x16x32_bf16 v[38:41], v[164:167], v[50:53], v[38:41]
	v_mov_b32_e32 v149, v150
	v_pk_add_f32 v[56:57], v[56:57], v[148:149]
	v_lshl_add_u64 v[90:91], v[90:91], 0, s[78:79]
	v_pk_add_f32 v[54:55], v[54:55], v[56:57]
	v_mfma_f32_16x16x32_bf16 v[34:37], v[168:171], v[50:53], v[34:37]
	v_add_f32_e32 v54, v54, v55
	ds_bpermute_b32 v55, v129, v54
	s_nop 0
	v_pk_mul_f32 v[40:41], v[142:143], v[40:41]
	v_mfma_f32_16x16x32_bf16 v[30:33], v[176:179], v[50:53], v[30:33]
	v_mul_f32_e64 v38, v140, v38
	v_mul_f32_e64 v39, v141, v39
	s_nop 0
	v_pk_mul_f32 v[36:37], v[146:147], v[36:37]
	v_pk_mul_f32 v[34:35], v[144:145], v[34:35]
	v_mfma_f32_16x16x32_bf16 v[26:29], v[180:183], v[50:53], v[26:29]
	s_waitcnt lgkmcnt(0)
	v_add_f32_e32 v50, v54, v55
	ds_bpermute_b32 v51, v130, v50
	s_waitcnt vmcnt(0)
	v_mov_b32_e32 v46, v220
	v_mov_b32_e32 v47, v221
	v_mov_b32_e32 v48, v222
	v_mov_b32_e32 v49, v223
	v_mov_b32_e32 v42, v224
	v_mov_b32_e32 v43, v225
	v_mov_b32_e32 v44, v226
	v_mov_b32_e32 v45, v227
	v_lshlrev_b32_e32 v52, 16, v48
	v_and_b32_e32 v53, 0xffff0000, v48
	v_lshlrev_b32_e32 v48, 16, v49
	v_and_b32_e32 v49, 0xffff0000, v49
	s_waitcnt lgkmcnt(0)
	v_add_f32_e32 v50, v50, v51
	ds_bpermute_b32 v51, v131, v50
	v_pk_mul_f32 v[32:33], v[186:187], v[32:33]
	v_pk_mul_f32 v[30:31], v[184:185], v[30:31]
	v_pk_mul_f32 v[28:29], v[190:191], v[28:29]
	v_pk_mul_f32 v[26:27], v[188:189], v[26:27]
	s_waitcnt lgkmcnt(0)
	v_add_f32_e32 v50, v50, v51
	v_fmamk_f32 v50, v50, 0x3c000000, v132
	v_rsq_f32_e32 v54, v50
	v_lshlrev_b32_e32 v50, 16, v46
	v_and_b32_e32 v51, 0xffff0000, v46
	v_lshlrev_b32_e32 v46, 16, v47
	v_pk_mul_f32 v[56:57], v[60:61], v[54:55] op_sel_hi:[1,0]
	v_and_b32_e32 v47, 0xffff0000, v47
	v_pk_mul_f32 v[56:57], v[4:5], v[56:57]
	v_pk_mul_f32 v[58:59], v[58:59], v[54:55] op_sel_hi:[1,0]
	v_pk_mul_f32 v[46:47], v[56:57], v[46:47]
	v_pk_mul_f32 v[56:57], v[64:65], v[54:55] op_sel_hi:[1,0]
	v_pk_mul_f32 v[58:59], v[2:3], v[58:59]
	v_pk_mul_f32 v[56:57], v[8:9], v[56:57]
	v_pk_mul_f32 v[50:51], v[58:59], v[50:51]
	v_pk_mul_f32 v[58:59], v[62:63], v[54:55] op_sel_hi:[1,0]
	v_pk_mul_f32 v[48:49], v[56:57], v[48:49]
	v_pk_mul_f32 v[56:57], v[68:69], v[54:55] op_sel_hi:[1,0]
	v_pk_mul_f32 v[58:59], v[6:7], v[58:59]
	v_cvt_pk_bf16_f32 v50, v50, v51
	v_cvt_pk_bf16_f32 v51, v46, v47
	s_waitcnt vmcnt(0)
	v_lshlrev_b32_e32 v46, 16, v42
	v_and_b32_e32 v47, 0xffff0000, v42
	v_lshlrev_b32_e32 v42, 16, v43
	v_and_b32_e32 v43, 0xffff0000, v43
	v_pk_mul_f32 v[56:57], v[12:13], v[56:57]
	v_pk_mul_f32 v[52:53], v[58:59], v[52:53]
	v_pk_mul_f32 v[58:59], v[66:67], v[54:55] op_sel_hi:[1,0]
	v_pk_mul_f32 v[42:43], v[56:57], v[42:43]
	v_pk_mul_f32 v[56:57], v[72:73], v[54:55] op_sel_hi:[1,0]
	v_pk_mul_f32 v[54:55], v[70:71], v[54:55] op_sel_hi:[1,0]
	v_cvt_pk_bf16_f32 v52, v52, v53
	v_cvt_pk_bf16_f32 v53, v48, v49
	v_lshlrev_b32_e32 v48, 16, v44
	v_and_b32_e32 v49, 0xffff0000, v44
	v_lshlrev_b32_e32 v44, 16, v45
	v_and_b32_e32 v45, 0xffff0000, v45
	v_pk_mul_f32 v[58:59], v[10:11], v[58:59]
	v_pk_mul_f32 v[54:55], v[14:15], v[54:55]
	v_pk_mul_f32 v[56:57], v[16:17], v[56:57]
	v_pk_mul_f32 v[46:47], v[58:59], v[46:47]
	v_pk_mul_f32 v[44:45], v[56:57], v[44:45]
	v_pk_mul_f32 v[48:49], v[54:55], v[48:49]
	v_cvt_pk_bf16_f32 v46, v46, v47
	v_cvt_pk_bf16_f32 v47, v42, v43
	v_cvt_pk_bf16_f32 v48, v48, v49
	v_cvt_pk_bf16_f32 v49, v44, v45
	v_mov_b32_e32 v18, v200
	v_mov_b32_e32 v19, v201
	v_mov_b32_e32 v20, v202
	v_mov_b32_e32 v21, v203
	v_mov_b32_e32 v22, v204
	v_mov_b32_e32 v23, v205
	v_mov_b32_e32 v24, v206
	v_mov_b32_e32 v25, v207
	v_mov_b32_e32 v103, v196
	v_mov_b32_e32 v104, v197
	v_mov_b32_e32 v107, v198
	v_mov_b32_e32 v109, v199
	v_mov_b32_e32 v110, v208
	v_mov_b32_e32 v111, v209
	v_mov_b32_e32 v112, v210
	v_mov_b32_e32 v113, v211
	v_lshlrev_b32_e32 v78, 16, v192
	v_and_b32_e32 v79, 0xffff0000, v192
	v_lshlrev_b32_e32 v80, 16, v193
	v_and_b32_e32 v81, 0xffff0000, v193
	v_lshlrev_b32_e32 v82, 16, v194
	v_and_b32_e32 v83, 0xffff0000, v194
	v_lshlrev_b32_e32 v84, 16, v195
	v_and_b32_e32 v85, 0xffff0000, v195
	v_lshl_add_u64 v[92:93], v[92:93], 0, s[76:77]
	s_cmp_lg_u32 s1, 0
	v_lshl_add_u64 v[94:95], v[94:95], 0, s[80:81]
	s_cbranch_scc0 .LBB0_603
; #define LAS __attribute__((address_space(3)))
; #define LBAR() do { asm volatile("s_waitcnt lgkmcnt(0)" ::: "memory"); __builtin_amdgcn_s_barrier(); asm volatile("" ::: "memory"); } while (0)
; __device__ __forceinline__ void gla_prompt_item(Frame& F, int b, int h) {
;     ...
;         const size_t t0 = tokb + 64 * (size_t)n;
;         f32x2 cs[4]; cs[0] = lg[0];
; #pragma unroll
;         for (int i = 1; i < 4; ++i) cs[i] = cs[i - 1] + lg[i];
;         *(LAS f32x2*)(L + G_TOT + (seg * 64 + 2 * kp) * 4) = cs[3];
; #pragma unroll
;         for (int i = 0; i < 2; ++i) { const int p_ = tid + 512 * i, row_ = p_ >> 4, c_ = p_ & 15; *(LAS v4u*)(L + G_V + row_ * G_VP + c_ * 16) = vv[i]; }
;         LBAR();
;         if (n > 0) {
; #pragma unroll
;             for (int i = 0; i < 2; ++i) *(v4u*)(MIX + (t0 - 64 + et) * DM + DA + h * 128 + 16 * evc + 8 * i) = outp[i];
;         }
;         f32x2 pre = {0.f, 0.f}, tot = {0.f, 0.f};
; #pragma unroll
;         for (int s = 0; s < 16; ++s) { const f32x2 v = *(const LAS f32x2*)(L + G_TOT + (s * 64 + 2 * kp) * 4); if (s < seg) pre += v; tot += v; }
;     ...
;         for (int i = 0; i < 2; ++i) gg[i] = *(const v4u*)(GBp + (t0 + et) * 512 + h * 128 + 16 * evc + 8 * i);
;         if (n + 1 < SEQ / 64 && var != 2) GLA_LOAD(n + 1);
.LBB0_595:
	v_pk_add_f32 v[140:141], v[80:81], v[78:79]
	v_add_u32_e32 v42, 0, v1
	v_pk_add_f32 v[142:143], v[140:141], v[82:83]
	v_add_u32_e32 v66, 0x13800, v42
	v_pk_add_f32 v[144:145], v[142:143], v[84:85]
	ds_write_b64 v99, v[144:145]
	ds_write_b128 v96, v[18:21] offset:18432
	ds_write_b128 v97, v[22:25] offset:18432
	s_waitcnt lgkmcnt(0)
	s_barrier
	v_lshl_add_u64 v[54:55], s[58:59], 0, v[94:95]
	ds_read2_b64 v[42:45], v66 offset1:32
	v_add_co_u32_e32 v54, vcc, s33, v54
	v_add_u32_e32 v139, 0x800, v66
	s_nop 0
	v_addc_co_u32_e32 v55, vcc, 0, v55, vcc
	global_store_dwordx4 v[54:55], v[50:53], off offset:1024
	global_store_dwordx4 v[54:55], v[46:49], off offset:1040
	v_lshl_add_u64 v[212:213], s[58:59], 0, v[92:93]
	v_lshl_add_u64 v[214:215], v[212:213], 0, s[74:75]
	v_add_co_u32_e32 v212, vcc, 0x27c10000, v212
	s_nop 1
	v_addc_co_u32_e32 v213, vcc, 0, v213, vcc
	global_load_dwordx4 v[220:223], v[212:213], off
	global_load_dwordx4 v[224:227], v[214:215], off offset:16
	s_cmp_eq_u32 s1, 1
	s_cbranch_scc1 .Lgla_nopf
	v_lshl_add_u64 v[212:213], s[58:59], 0, v[90:91]
	v_add_co_u32_e32 v214, vcc, 0x1f410000, v212
	s_nop 1
	v_addc_co_u32_e32 v215, vcc, 0, v213, vcc
	v_add_co_u32_e32 v216, vcc, 0x16c10000, v212
	s_nop 1
	v_addc_co_u32_e32 v217, vcc, 0, v213, vcc
	v_add_co_u32_e32 v218, vcc, 0x18e10000, v212
	s_nop 1
	v_addc_co_u32_e32 v219, vcc, 0, v213, vcc
	global_load_dword v192, v[214:215], off
	global_load_dword v196, v[216:217], off
	global_load_dword v193, v[214:215], off offset:512
	global_load_dword v197, v[216:217], off offset:512
	global_load_dword v194, v[214:215], off offset:1024
	global_load_dword v198, v[216:217], off offset:1024
	global_load_dword v199, v[216:217], off offset:1536
	global_load_dword v195, v[214:215], off offset:1536
	v_lshl_add_u64 v[212:213], s[58:59], 0, v[88:89]
	v_lshl_add_u64 v[214:215], s[58:59], 0, v[86:87]
	global_load_dwordx4 v[200:203], v[212:213], off
	global_load_dwordx4 v[204:207], v[214:215], off
	global_load_dword v208, v[218:219], off
	global_load_dword v209, v[218:219], off offset:512
	global_load_dword v210, v[218:219], off offset:1024
	global_load_dword v211, v[218:219], off offset:1536
.Lgla_nopf:
	ds_read2_b64 v[46:49], v66 offset0:64 offset1:96
	s_waitcnt lgkmcnt(1)
	v_pk_add_f32 v[42:43], v[42:43], 0 op_sel_hi:[1,0]
	v_lshlrev_b32_e32 v152, 16, v103
	v_cndmask_b32_e64 v51, 0, v43, s[4:5]
	v_cndmask_b32_e64 v50, 0, v42, s[4:5]
	v_pk_add_f32 v[52:53], v[44:45], v[50:51]
	v_and_b32_e32 v153, 0xffff0000, v103
	v_cndmask_b32_e64 v55, v51, v53, s[6:7]
	v_cndmask_b32_e64 v54, v50, v52, s[6:7]
	ds_read2_b64 v[50:53], v66 offset0:128 offset1:160
	s_waitcnt lgkmcnt(1)
	v_pk_add_f32 v[56:57], v[46:47], v[54:55]
	s_nop 0
	v_cndmask_b32_e64 v55, v55, v57, s[8:9]
	v_cndmask_b32_e64 v54, v54, v56, s[8:9]
	v_pk_add_f32 v[56:57], v[48:49], v[54:55]
	s_nop 0
	v_cndmask_b32_e64 v59, v55, v57, s[10:11]
	v_cndmask_b32_e64 v58, v54, v56, s[10:11]
	ds_read2_b64 v[54:57], v66 offset0:192 offset1:224
	s_waitcnt lgkmcnt(1)
	v_pk_add_f32 v[60:61], v[50:51], v[58:59]
	s_nop 0
	v_cndmask_b32_e64 v59, v59, v61, s[12:13]
	v_cndmask_b32_e64 v58, v58, v60, s[12:13]
	v_pk_add_f32 v[60:61], v[52:53], v[58:59]
	s_nop 0
	v_cndmask_b32_e64 v63, v59, v61, s[14:15]
	v_cndmask_b32_e64 v62, v58, v60, s[14:15]
	ds_read2_b64 v[58:61], v139 offset1:32
	s_waitcnt lgkmcnt(1)
	v_pk_add_f32 v[64:65], v[54:55], v[62:63]
	s_nop 0
	v_cndmask_b32_e64 v63, v63, v65, s[16:17]
	v_cndmask_b32_e64 v62, v62, v64, s[16:17]
	v_pk_add_f32 v[64:65], v[56:57], v[62:63]
	s_nop 0
	v_cndmask_b32_e64 v67, v63, v65, s[18:19]
	v_cndmask_b32_e64 v66, v62, v64, s[18:19]
	ds_read2_b64 v[62:65], v139 offset0:64 offset1:96
	s_waitcnt lgkmcnt(1)
	v_pk_add_f32 v[68:69], v[58:59], v[66:67]
	s_nop 0
	v_cndmask_b32_e64 v67, v67, v69, s[20:21]
	v_cndmask_b32_e64 v66, v66, v68, s[20:21]
	v_pk_add_f32 v[68:69], v[60:61], v[66:67]
	s_nop 0
	v_cndmask_b32_e64 v71, v67, v69, s[22:23]
	v_cndmask_b32_e64 v70, v66, v68, s[22:23]
	ds_read2_b64 v[66:69], v139 offset0:128 offset1:160
	s_waitcnt lgkmcnt(1)
	v_pk_add_f32 v[72:73], v[62:63], v[70:71]
	s_nop 0
	v_cndmask_b32_e64 v71, v71, v73, s[24:25]
	v_cndmask_b32_e64 v70, v70, v72, s[24:25]
	v_pk_add_f32 v[72:73], v[64:65], v[70:71]
	s_nop 0
	v_cndmask_b32_e64 v147, v71, v73, s[26:27]
	v_cndmask_b32_e64 v146, v70, v72, s[26:27]
	ds_read2_b64 v[70:73], v139 offset0:192 offset1:224
	s_waitcnt lgkmcnt(1)
	v_pk_add_f32 v[148:149], v[66:67], v[146:147]
	s_nop 0
	v_cndmask_b32_e64 v147, v147, v149, s[28:29]
	v_cndmask_b32_e64 v146, v146, v148, s[28:29]
	v_pk_add_f32 v[148:149], v[68:69], v[146:147]
	s_nop 0
	v_cndmask_b32_e64 v147, v147, v149, s[30:31]
	v_cndmask_b32_e64 v146, v146, v148, s[30:31]
	s_waitcnt lgkmcnt(0)
; #define LAS __attribute__((address_space(3)))
; #define LBAR() do { asm volatile("s_waitcnt lgkmcnt(0)" ::: "memory"); __builtin_amdgcn_s_barrier(); asm volatile("" ::: "memory"); } while (0)
; __device__ __forceinline__ unsigned pk2(float lo, float hi) { typedef float f2 __attribute__((ext_vector_type(2))); typedef __bf16 b2 __attribute__((ext_vector_type(2))); f2 v = {lo, hi}; b2 b = __builtin_convertvector(v, b2); return __builtin_bit_cast(unsigned, b); }
; __device__ __forceinline__ void gla_prompt_item(Frame& F, int b, int h) {
;     ...
;         f32x2 pre = {0.f, 0.f}, tot = {0.f, 0.f};
; #pragma unroll
;         for (int s = 0; s < 16; ++s) { const f32x2 v = *(const LAS f32x2*)(L + G_TOT + (s * 64 + 2 * kp) * 4); if (s < seg) pre += v; tot += v; }
; #pragma unroll
;         for (int i = 0; i < 4; ++i) {
;             f32x2 bb = pre + cs[i]; bb.x = fmaxf(bb.x, -80.f); bb.y = fmaxf(bb.y, -80.f);
;             const float ep0 = fast_exp(bb.x), ep1 = fast_exp(bb.y), em0 = fast_exp(-bb.x), em1 = fast_exp(-bb.y);
;             const int t = 4 * seg + i;
;             *(LAS unsigned*)(L + G_QT + t * G_RP + kp * 4) = pk2(bflo(qv[i]) * ep0, bfhi(qv[i]) * ep1);
;             *(LAS unsigned*)(L + G_KT + t * G_RP + kp * 4) = pk2(bflo(kv[i]) * em0, bfhi(kv[i]) * em1);
;         }
;         if (seg == 0) { f32x2 dd; dd.x = fast_exp(fmaxf(tot.x, -80.f)); dd.y = fast_exp(fmaxf(tot.y, -80.f)); *(LAS f32x2*)(L + G_D + 2 * kp * 4) = dd; }
; #pragma unroll
;         for (int i = 0; i < 2; ++i) gg[i] = *(const v4u*)(GBp + (t0 + et) * 512 + h * 128 + 16 * evc + 8 * i);
;         if (n + 1 < SEQ / 64 && var != 2) GLA_LOAD(n + 1);
;         LBAR();
;         if (var != 3) {
;             const int tb = w >> 1;
; #pragma unroll
;             for (int q2 = 0; q2 < 2; ++q2) {
;                 const int sb = 2 * (w & 1) + q2;
;                 f32x4 c4 = {0.f, 0.f, 0.f, 0.f};
;                 if (sb <= tb) {
; #pragma unroll
;                     for (int sp = 0; sp < 2; ++sp) {
;                         const bf16x8 a = *(const LAS bf16x8*)(L + G_KT + (16 * sb + i16) * G_RP + (32 * sp + 8 * g) * 2);
;                         const bf16x8 bq = *(const LAS bf16x8*)(L + G_QT + (16 * tb + i16) * G_RP + (32 * sp + 8 * g) * 2);
;                         c4 = MFMA16(a, bq, c4);
;                     }
;                 }
	v_pk_add_f32 v[148:149], v[70:71], v[146:147]
	s_nop 0
	v_cndmask_b32_e64 v147, v147, v149, s[34:35]
	v_cndmask_b32_e64 v146, v146, v148, s[34:35]
	v_pk_add_f32 v[148:149], v[72:73], v[146:147]
	s_nop 0
	v_cndmask_b32_e64 v147, v147, v149, s[36:37]
	v_cndmask_b32_e64 v146, v146, v148, s[36:37]
	v_pk_add_f32 v[148:149], v[146:147], v[78:79]
	v_pk_add_f32 v[140:141], v[140:141], v[146:147]
	v_max_f32_e32 v139, 0xc2a00000, v148
	v_max_f32_e32 v151, 0xc2a00000, v149
	v_mul_f32_e32 v148, 0x3fb8aa3b, v139
	v_mul_f32_e32 v149, 0x3fb8aa3b, v151
	v_exp_f32_e32 v148, v148
	v_exp_f32_e32 v149, v149
	v_mul_f32_e32 v139, 0xbfb8aa3b, v139
	v_exp_f32_e32 v150, v139
	v_mul_f32_e32 v139, 0xbfb8aa3b, v151
	v_exp_f32_e32 v151, v139
	v_pk_mul_f32 v[148:149], v[148:149], v[152:153]
	s_nop 0
	v_cvt_pk_bf16_f32 v139, v148, v149
	v_lshlrev_b32_e32 v148, 16, v110
	v_and_b32_e32 v149, 0xffff0000, v110
	v_pk_mul_f32 v[148:149], v[150:151], v[148:149]
	v_lshlrev_b32_e32 v150, 16, v104
	v_cvt_pk_bf16_f32 v152, v148, v149
	v_max_f32_e32 v148, 0xc2a00000, v140
	v_max_f32_e32 v149, 0xc2a00000, v141
	v_mul_f32_e32 v140, 0x3fb8aa3b, v148
	v_mul_f32_e32 v141, 0x3fb8aa3b, v149
	v_exp_f32_e32 v140, v140
	v_exp_f32_e32 v141, v141
	v_mul_f32_e32 v148, 0xbfb8aa3b, v148
	v_mul_f32_e32 v149, 0xbfb8aa3b, v149
	v_exp_f32_e32 v148, v148
	v_exp_f32_e32 v149, v149
	v_and_b32_e32 v151, 0xffff0000, v104
	v_pk_mul_f32 v[140:141], v[140:141], v[150:151]
	v_add_u32_e32 v150, 0x2400, v98
	v_cvt_pk_bf16_f32 v140, v140, v141
	ds_write2_b32 v98, v139, v140 offset1:36
	v_lshlrev_b32_e32 v140, 16, v111
	v_and_b32_e32 v141, 0xffff0000, v111
	v_pk_mul_f32 v[140:141], v[148:149], v[140:141]
	v_lshlrev_b32_e32 v148, 16, v107
	v_cvt_pk_bf16_f32 v139, v140, v141
	v_pk_add_f32 v[140:141], v[142:143], v[146:147]
	ds_write2_b32 v150, v152, v139 offset1:36
	v_max_f32_e32 v139, 0xc2a00000, v140
	v_max_f32_e32 v143, 0xc2a00000, v141
	v_mul_f32_e32 v140, 0x3fb8aa3b, v139
	v_mul_f32_e32 v141, 0x3fb8aa3b, v143
	v_exp_f32_e32 v140, v140
	v_exp_f32_e32 v141, v141
	v_mul_f32_e32 v139, 0xbfb8aa3b, v139
	v_exp_f32_e32 v142, v139
	v_mul_f32_e32 v139, 0xbfb8aa3b, v143
	v_exp_f32_e32 v143, v139
	v_and_b32_e32 v149, 0xffff0000, v107
	v_pk_mul_f32 v[140:141], v[140:141], v[148:149]
	s_nop 0
	v_cvt_pk_bf16_f32 v139, v140, v141
	v_lshlrev_b32_e32 v140, 16, v112
	v_and_b32_e32 v141, 0xffff0000, v112
	v_pk_mul_f32 v[140:141], v[142:143], v[140:141]
	s_nop 0
	v_cvt_pk_bf16_f32 v148, v140, v141
	v_pk_add_f32 v[140:141], v[144:145], v[146:147]
	v_lshlrev_b32_e32 v144, 16, v109
	v_max_f32_e32 v142, 0xc2a00000, v140
	v_max_f32_e32 v143, 0xc2a00000, v141
	v_mul_f32_e32 v140, 0x3fb8aa3b, v142
	v_mul_f32_e32 v141, 0x3fb8aa3b, v143
	v_exp_f32_e32 v140, v140
	v_exp_f32_e32 v141, v141
	v_mul_f32_e32 v142, 0xbfb8aa3b, v142
	v_mul_f32_e32 v143, 0xbfb8aa3b, v143
	v_exp_f32_e32 v142, v142
	v_exp_f32_e32 v143, v143
	v_and_b32_e32 v145, 0xffff0000, v109
	v_pk_mul_f32 v[140:141], v[140:141], v[144:145]
	s_nop 0
	v_cvt_pk_bf16_f32 v140, v140, v141
	ds_write2_b32 v98, v139, v140 offset0:72 offset1:108
	v_lshlrev_b32_e32 v140, 16, v113
	v_and_b32_e32 v141, 0xffff0000, v113
	v_pk_mul_f32 v[140:141], v[142:143], v[140:141]
	s_nop 0
	v_cvt_pk_bf16_f32 v139, v140, v141
	ds_write2_b32 v150, v148, v139 offset0:72 offset1:108
	s_and_saveexec_b64 s[82:83], s[54:55]
	s_cbranch_execz .LBB0_597
	v_pk_add_f32 v[42:43], v[42:43], v[44:45]
	v_add_u32_e32 v44, 0x14800, v100
	v_pk_add_f32 v[42:43], v[42:43], v[46:47]
	s_nop 0
	v_pk_add_f32 v[42:43], v[42:43], v[48:49]
	s_nop 0
	v_pk_add_f32 v[42:43], v[42:43], v[50:51]
	s_nop 0
	v_pk_add_f32 v[42:43], v[42:43], v[52:53]
	s_nop 0
	v_pk_add_f32 v[42:43], v[42:43], v[54:55]
	s_nop 0
	v_pk_add_f32 v[42:43], v[42:43], v[56:57]
	s_nop 0
	v_pk_add_f32 v[42:43], v[42:43], v[58:59]
	s_nop 0
	v_pk_add_f32 v[42:43], v[42:43], v[60:61]
	s_nop 0
	v_pk_add_f32 v[42:43], v[42:43], v[62:63]
	s_nop 0
	v_pk_add_f32 v[42:43], v[42:43], v[64:65]
	s_nop 0
	v_pk_add_f32 v[42:43], v[42:43], v[66:67]
	s_nop 0
	v_pk_add_f32 v[42:43], v[42:43], v[68:69]
	s_nop 0
	v_pk_add_f32 v[42:43], v[42:43], v[70:71]
	s_nop 0
	v_pk_add_f32 v[42:43], v[42:43], v[72:73]
	s_nop 0
	v_max_f32_e32 v42, 0xc2a00000, v42
	v_max_f32_e32 v43, 0xc2a00000, v43
	v_mul_f32_e32 v42, 0x3fb8aa3b, v42
	v_mul_f32_e32 v43, 0x3fb8aa3b, v43
	v_exp_f32_e32 v42, v42
	v_exp_f32_e32 v43, v43
	ds_write_b64 v44, v[42:43]
.LBB0_597:
	s_or_b64 exec, exec, s[82:83]
.LBB0_599:
	s_waitcnt lgkmcnt(0)
	s_barrier
	v_mov_b32_e32 v50, 0
	s_andn2_b64 vcc, exec, s[70:71]
	v_add_u32_e32 v56, v105, v115
	v_mov_b32_e32 v52, 0
	v_mov_b32_e32 v53, 0
	v_mov_b32_e32 v54, 0
	v_mov_b32_e32 v55, 0
	s_cbranch_vccnz .LBB0_601
	v_add_u32_e32 v51, v133, v106
	ds_read_b128 v[52:55], v51 offset:9216
	v_add_u32_e32 v51, v133, v115
	ds_read_b128 v[58:61], v51 offset:9216
	ds_read_b128 v[62:65], v108
	ds_read_b128 v[66:69], v56
	s_waitcnt lgkmcnt(1)
	v_mfma_f32_16x16x32_bf16 v[52:55], v[52:55], v[62:65], 0
	s_waitcnt lgkmcnt(0)
	v_mfma_f32_16x16x32_bf16 v[52:55], v[58:61], v[66:69], v[52:55]

; __device__ __forceinline__ float fast_exp2(float x) { return __builtin_amdgcn_exp2f(x); }
; #define INP(k) (args_ptr()->in[k])
; #define AS_LDQ(tt) ({ const v2u r_ = *(const v2u*)(Qp + (row0 + (tt)) * DA + h * 64 + 4 * c); (f32x4){bflo(r_.x), bfhi(r_.x), bflo(r_.y), bfhi(r_.y)}; })
; #define AS_ROW(idx_, kv_, vv_) do { const int ix_ = (idx_); const bool fr_ = ix_ >= WIN;        \
;         const float* kp_ = fr_ ? nK + (size_t)(ix_ - WIN) * (HA * HD) : cK + (size_t)ix_ * (HA * HD); const float* vp_ = fr_ ? nV + (size_t)(ix_ - WIN) * (HA * HD) : cV + (size_t)ix_ * (HA * HD); \
;         kv_ = NTLD((const f32x4*)kp_); vv_ = NTLD((const f32x4*)vp_); } while (0)
; #define AS_DOT(kv_, q_) ({ float d_ = ((kv_)[0] * (q_)[0] + (kv_)[1] * (q_)[1]) + ((kv_)[2] * (q_)[2] + (kv_)[3] * (q_)[3]); \
;         d_ += AS_ROR(d_, 8); d_ += AS_ROR(d_, 4); d_ += AS_ROR(d_, 2); d_ += AS_ROR(d_, 1); d_; })
; __device__ __forceinline__ void attn_sample_item(Frame& F, int b, int h) {
;     ...
;     const float* cK = INP(I_CK) + ((size_t)b * WIN * HA + h) * HD + 4 * c; const float* cV = INP(I_CV) + ((size_t)b * WIN * HA + h) * HD + 4 * c;
;     const float* nK = F.out + OUT_KNEW + ((size_t)b * ST * HA + h) * HD + 4 * c; const float* nV = F.out + OUT_VNEW + ((size_t)b * ST * HA + h) * HD + 4 * c;
;     ...
;     {
;         const f32x4 qown = AS_LDQ(w);
;         f32x4 o16 = {0.f, 0.f, 0.f, 0.f}; float l16 = 0.f;
; #pragma unroll 1
;         for (int it0 = 0; it0 < 32; it0 += 4) {
;             f32x4 kv[4], vv[4];
; #pragma unroll
;             for (int u = 0; u < 4; ++u) AS_ROW(WIN + w - 16 * (4 * (it0 + u) + g4), kv[u], vv[u]);
; #pragma unroll
;             for (int u = 0; u < 4; ++u) { const float p = fast_exp2(AS_DOT(kv[u], qown) - mref); l16 += p; o16 += vv[u] * p; }
;         }
.LBB0_786:
	s_andn2_b64 vcc, exec, s[6:7]
	s_cbranch_vccnz .LBB0_850
	s_andn2_b64 vcc, exec, s[24:25]
	s_cbranch_vccnz .LBB0_850
	v_mov_b32_e32 v5, v0
	s_and_b32 s44, s0, -8
	v_readfirstlane_b32 s1, v5
	s_ashr_i32 s6, s0, 3
	s_ashr_i32 s1, s1, 6
	s_ashr_i32 s45, s44, 31
	s_add_u32 s42, s44, 0x10000
	s_addc_u32 s43, s45, 0
	s_mov_b64 s[8:9], s[92:93]
	s_lshl_b32 s0, s0, 6
	global_load_dword v122, v23, s[26:27]
	s_ashr_i32 s7, s6, 31
	s_and_b32 s0, s0, 0x1c0
	v_mov_b64_e32 v[2:3], s[8:9]
	s_lshl_b64 s[8:9], s[6:7], 22
	s_lshl_b32 s14, s0, 2
	s_mov_b64 s[12:13], s[92:93]
	s_lshl_b64 s[6:7], s[6:7], 14
	flat_load_dwordx2 v[10:11], v[2:3] offset:16
	s_or_b32 s8, s8, s14
	s_or_b32 s6, s6, s14
	v_mov_b64_e32 v[2:3], s[12:13]
	s_add_u32 s12, s55, s6
	s_addc_u32 s13, s63, s7
	s_add_u32 s6, s64, s6
	s_addc_u32 s7, s65, s7
	s_ashr_i32 s14, s1, 31
	s_add_u32 s38, s42, s1
	s_addc_u32 s39, s43, s14
	s_lshl_b64 s[40:41], s[38:39], 9
	s_lshl_b64 s[46:47], s[38:39], 10
	s_add_u32 s33, s53, s46
	s_addc_u32 s47, s54, s47
	s_lshl_b32 s46, s0, 1
	v_and_b32_e32 v121, 15, v5
	s_add_u32 s46, s33, s46
	flat_load_dwordx2 v[12:13], v[2:3] offset:24
	s_addc_u32 s47, s47, 0
	v_lshlrev_b32_e32 v2, 3, v121
	global_load_dwordx2 v[14:15], v2, s[46:47]
	v_bfe_u32 v123, v5, 4, 2
	v_lshlrev_b32_e32 v22, 4, v121
	v_lshlrev_b32_e32 v125, 4, v123
	v_mov_b32_e32 v7, 0
	v_lshrrev_b32_e32 v124, 4, v5
	v_mov_b32_e32 v5, s14
	v_sub_co_u32_e32 v8, vcc, s1, v125
	s_mov_b32 s33, 4
	s_mov_b32 s46, 0xfffffe00
	s_mov_b32 s47, -1
	v_mov_b32_e32 v2, 0
	v_mov_b32_e32 v4, 0
	v_mov_b32_e32 v3, v7
	v_lshlrev_b32_e32 v24, 2, v121
	v_sub_u32_e32 v6, s1, v125
	v_lshl_add_u64 v[34:35], s[12:13], 0, v[22:23]
	v_lshl_add_u64 v[36:37], s[6:7], 0, v[22:23]
	v_subbrev_co_u32_e32 v9, vcc, 0, v5, vcc
	v_mov_b32_e32 v5, v7
	s_waitcnt vmcnt(0) lgkmcnt(0)
	v_lshl_add_u64 v[10:11], v[10:11], 0, s[8:9]
	v_lshl_add_u64 v[32:33], v[10:11], 0, v[22:23]
	v_lshl_add_u64 v[10:11], v[12:13], 0, s[8:9]
	v_lshl_add_u64 v[30:31], v[10:11], 0, v[22:23]
	v_lshlrev_b32_e32 v26, 16, v14
	v_and_b32_e32 v27, 0xffff0000, v15
	v_and_b32_e32 v28, 0xffff0000, v14
	v_lshlrev_b32_e32 v29, 16, v15
.LBB0_789:
	v_add_u32_e32 v18, s46, v6
	v_lshl_add_u64 v[10:11], v[8:9], 0, s[46:47]
	v_add_u32_e32 v19, 0x800, v18
	v_add_u32_e32 v20, 0x7c0, v18
	v_add_u32_e32 v21, 0x780, v18
	v_add_u32_e32 v38, 0x740, v18
	v_lshl_add_u64 v[12:13], v[10:11], 0, s[28:29]
	v_subrev_u32_e32 v22, 64, v18
	v_lshl_add_u64 v[14:15], v[10:11], 0, s[30:31]
	v_add_u32_e32 v42, 0xffffff80, v18
	v_lshl_add_u64 v[16:17], v[10:11], 0, s[34:35]
	v_add_u32_e32 v46, 0xffffff40, v18
	v_lshl_add_u64 v[10:11], v[10:11], 0, s[36:37]
	v_cmp_lt_i32_e32 vcc, s72, v19
	v_cmp_lt_i32_e64 s[6:7], s72, v20
	v_cmp_lt_i32_e64 s[8:9], s72, v21
	v_cmp_lt_i32_e64 s[12:13], s72, v38
	v_cndmask_b32_e32 v12, v12, v18, vcc
	v_cndmask_b32_e64 v15, v15, 0, s[6:7]
	v_cndmask_b32_e64 v17, v17, 0, s[8:9]
	v_cndmask_b32_e64 v11, v11, 0, s[12:13]
	v_cndmask_b32_e64 v13, v13, 0, vcc
	v_cndmask_b32_e64 v14, v14, v22, s[6:7]
	v_cndmask_b32_e64 v16, v16, v42, s[8:9]
	v_cndmask_b32_e64 v10, v10, v46, s[12:13]
	v_cndmask_b32_e32 v19, v33, v35, vcc
	v_cndmask_b32_e32 v18, v32, v34, vcc
	v_cndmask_b32_e64 v39, v33, v35, s[6:7]
	v_cndmask_b32_e64 v38, v32, v34, s[6:7]
	v_cndmask_b32_e64 v43, v33, v35, s[8:9]
	v_cndmask_b32_e64 v42, v32, v34, s[8:9]
	v_cndmask_b32_e64 v47, v33, v35, s[12:13]
	v_cndmask_b32_e64 v46, v32, v34, s[12:13]
	v_lshlrev_b64 v[12:13], 11, v[12:13]
	v_lshlrev_b64 v[14:15], 11, v[14:15]
	v_lshlrev_b64 v[50:51], 11, v[16:17]
	v_lshlrev_b64 v[52:53], 11, v[10:11]
	v_cndmask_b32_e32 v21, v31, v37, vcc
	v_cndmask_b32_e32 v20, v30, v36, vcc
	v_cndmask_b32_e64 v41, v31, v37, s[6:7]
	v_cndmask_b32_e64 v40, v30, v36, s[6:7]
	v_lshl_add_u64 v[10:11], v[18:19], 0, v[12:13]
	v_lshl_add_u64 v[16:17], v[38:39], 0, v[14:15]
	v_lshl_add_u64 v[18:19], v[42:43], 0, v[50:51]
	v_lshl_add_u64 v[38:39], v[46:47], 0, v[52:53]
	v_lshl_add_u64 v[54:55], v[20:21], 0, v[12:13]
	v_lshl_add_u64 v[56:57], v[40:41], 0, v[14:15]
	global_load_dwordx4 v[10:13], v[10:11], off nt
	s_nop 0
	global_load_dwordx4 v[14:17], v[16:17], off nt
	s_nop 0
	global_load_dwordx4 v[18:21], v[18:19], off nt
	s_nop 0
	global_load_dwordx4 v[38:41], v[38:39], off nt
	v_cndmask_b32_e64 v45, v31, v37, s[8:9]
	v_cndmask_b32_e64 v44, v30, v36, s[8:9]
	v_cndmask_b32_e64 v49, v31, v37, s[12:13]
	v_cndmask_b32_e64 v48, v30, v36, s[12:13]
	v_lshl_add_u64 v[50:51], v[44:45], 0, v[50:51]
	v_lshl_add_u64 v[58:59], v[48:49], 0, v[52:53]
	global_load_dwordx4 v[42:45], v[54:55], off nt
	global_load_dwordx4 v[46:49], v[56:57], off nt
	s_nop 0
	global_load_dwordx4 v[50:53], v[50:51], off nt
	s_nop 0
	global_load_dwordx4 v[54:57], v[58:59], off nt
	s_add_i32 s33, s33, 4
	s_add_u32 s46, s46, 0xffffff00
	s_addc_u32 s47, s47, -1
	v_add_u32_e32 v184, s46, v6
	v_lshl_add_u64 v[176:177], v[8:9], 0, s[46:47]
	v_add_u32_e32 v185, 0x800, v184
	v_add_u32_e32 v186, 0x7c0, v184
	v_add_u32_e32 v187, 0x780, v184
	v_add_u32_e32 v190, 0x740, v184
	v_lshl_add_u64 v[178:179], v[176:177], 0, s[28:29]
	v_subrev_u32_e32 v188, 64, v184
	v_lshl_add_u64 v[180:181], v[176:177], 0, s[30:31]
	v_add_u32_e32 v194, 0xffffff80, v184
	v_lshl_add_u64 v[182:183], v[176:177], 0, s[34:35]
	v_add_u32_e32 v198, 0xffffff40, v184
	v_lshl_add_u64 v[176:177], v[176:177], 0, s[36:37]
	v_cmp_lt_i32_e32 vcc, s72, v185
	v_cmp_lt_i32_e64 s[6:7], s72, v186
	v_cmp_lt_i32_e64 s[8:9], s72, v187
	v_cmp_lt_i32_e64 s[12:13], s72, v190
	v_cndmask_b32_e32 v178, v178, v184, vcc
	v_cndmask_b32_e64 v181, v181, 0, s[6:7]
	v_cndmask_b32_e64 v183, v183, 0, s[8:9]
	v_cndmask_b32_e64 v177, v177, 0, s[12:13]
; __device__ __forceinline__ float fast_exp2(float x) { return __builtin_amdgcn_exp2f(x); }
; #define AS_ROW(idx_, kv_, vv_) do { const int ix_ = (idx_); const bool fr_ = ix_ >= WIN;        \
;         const float* kp_ = fr_ ? nK + (size_t)(ix_ - WIN) * (HA * HD) : cK + (size_t)ix_ * (HA * HD); const float* vp_ = fr_ ? nV + (size_t)(ix_ - WIN) * (HA * HD) : cV + (size_t)ix_ * (HA * HD); \
;         kv_ = NTLD((const f32x4*)kp_); vv_ = NTLD((const f32x4*)vp_); } while (0)
; #define AS_DOT(kv_, q_) ({ float d_ = ((kv_)[0] * (q_)[0] + (kv_)[1] * (q_)[1]) + ((kv_)[2] * (q_)[2] + (kv_)[3] * (q_)[3]); \
;         d_ += AS_ROR(d_, 8); d_ += AS_ROR(d_, 4); d_ += AS_ROR(d_, 2); d_ += AS_ROR(d_, 1); d_; })
; __device__ __forceinline__ void attn_sample_item(Frame& F, int b, int h) {
;     ...
; #pragma unroll 1
;         for (int it0 = 0; it0 < 32; it0 += 4) {
;             f32x4 kv[4], vv[4];
; #pragma unroll
;             for (int u = 0; u < 4; ++u) AS_ROW(WIN + w - 16 * (4 * (it0 + u) + g4), kv[u], vv[u]);
; #pragma unroll
;             for (int u = 0; u < 4; ++u) { const float p = fast_exp2(AS_DOT(kv[u], qown) - mref); l16 += p; o16 += vv[u] * p; }
;         }
	v_cndmask_b32_e64 v179, v179, 0, vcc
	v_cndmask_b32_e64 v180, v180, v188, s[6:7]
	v_cndmask_b32_e64 v182, v182, v194, s[8:9]
	v_cndmask_b32_e64 v176, v176, v198, s[12:13]
	v_cndmask_b32_e32 v185, v33, v35, vcc
	v_cndmask_b32_e32 v184, v32, v34, vcc
	v_cndmask_b32_e64 v191, v33, v35, s[6:7]
	v_cndmask_b32_e64 v190, v32, v34, s[6:7]
	v_cndmask_b32_e64 v195, v33, v35, s[8:9]
	v_cndmask_b32_e64 v194, v32, v34, s[8:9]
	v_cndmask_b32_e64 v199, v33, v35, s[12:13]
	v_cndmask_b32_e64 v198, v32, v34, s[12:13]
	v_lshlrev_b64 v[178:179], 11, v[178:179]
	v_lshlrev_b64 v[180:181], 11, v[180:181]
	v_lshlrev_b64 v[202:203], 11, v[182:183]
	v_lshlrev_b64 v[204:205], 11, v[176:177]
	v_cndmask_b32_e32 v187, v31, v37, vcc
	v_cndmask_b32_e32 v186, v30, v36, vcc
	v_cndmask_b32_e64 v193, v31, v37, s[6:7]
	v_cndmask_b32_e64 v192, v30, v36, s[6:7]
	v_lshl_add_u64 v[176:177], v[184:185], 0, v[178:179]
	v_lshl_add_u64 v[182:183], v[190:191], 0, v[180:181]
	v_lshl_add_u64 v[184:185], v[194:195], 0, v[202:203]
	v_lshl_add_u64 v[190:191], v[198:199], 0, v[204:205]
	v_lshl_add_u64 v[206:207], v[186:187], 0, v[178:179]
	v_lshl_add_u64 v[208:209], v[192:193], 0, v[180:181]
	global_load_dwordx4 v[176:179], v[176:177], off nt
	s_nop 0
	global_load_dwordx4 v[180:183], v[182:183], off nt
	s_nop 0
	global_load_dwordx4 v[184:187], v[184:185], off nt
	s_nop 0
	global_load_dwordx4 v[190:193], v[190:191], off nt
	v_cndmask_b32_e64 v197, v31, v37, s[8:9]
	v_cndmask_b32_e64 v196, v30, v36, s[8:9]
	v_cndmask_b32_e64 v201, v31, v37, s[12:13]
	v_cndmask_b32_e64 v200, v30, v36, s[12:13]
	v_lshl_add_u64 v[202:203], v[196:197], 0, v[202:203]
	v_lshl_add_u64 v[210:211], v[200:201], 0, v[204:205]
	global_load_dwordx4 v[194:197], v[206:207], off nt
	global_load_dwordx4 v[198:201], v[208:209], off nt
	s_nop 0
	global_load_dwordx4 v[202:205], v[202:203], off nt
	s_nop 0
	global_load_dwordx4 v[206:209], v[210:211], off nt
	s_add_i32 s33, s33, 4
	s_add_u32 s46, s46, 0xffffff00
	s_addc_u32 s47, s47, -1
	s_cmp_gt_u32 s33, 27
	s_waitcnt vmcnt(0)
	v_mov_b32_e32 v58, v11
	v_mov_b32_e32 v11, v13
	v_mov_b32_e32 v59, v12
	v_mov_b32_e32 v12, v15
	v_mov_b32_e32 v15, v17
	v_pk_mul_f32 v[10:11], v[10:11], v[26:27]
	v_mov_b32_e32 v13, v16
	v_mov_b32_e32 v16, v19
	v_mov_b32_e32 v19, v21
	v_pk_mul_f32 v[14:15], v[14:15], v[26:27]
	v_pk_fma_f32 v[10:11], v[58:59], v[28:29], v[10:11]
	v_mov_b32_e32 v17, v20
	v_mov_b32_e32 v20, v39
	v_mov_b32_e32 v39, v41
	v_pk_mul_f32 v[18:19], v[18:19], v[26:27]
	v_pk_fma_f32 v[12:13], v[12:13], v[28:29], v[14:15]
	v_add_f32_e32 v10, v10, v11
	v_mov_b32_e32 v21, v40
	v_pk_mul_f32 v[38:39], v[38:39], v[26:27]
	v_pk_fma_f32 v[14:15], v[16:17], v[28:29], v[18:19]
	v_add_f32_e32 v11, v12, v13
	v_add_f32_dpp v10, v10, v10 row_ror:8 row_mask:0xf bank_mask:0xf bound_ctrl:1
	v_pk_fma_f32 v[16:17], v[20:21], v[28:29], v[38:39]
	v_add_f32_e32 v12, v14, v15
	v_add_f32_dpp v11, v11, v11 row_ror:8 row_mask:0xf bank_mask:0xf bound_ctrl:1
	v_add_f32_dpp v10, v10, v10 row_ror:4 row_mask:0xf bank_mask:0xf bound_ctrl:1
	v_add_f32_e32 v13, v16, v17
	v_add_f32_dpp v12, v12, v12 row_ror:8 row_mask:0xf bank_mask:0xf bound_ctrl:1
	v_add_f32_dpp v11, v11, v11 row_ror:4 row_mask:0xf bank_mask:0xf bound_ctrl:1
	v_add_f32_dpp v10, v10, v10 row_ror:2 row_mask:0xf bank_mask:0xf bound_ctrl:1
	v_add_f32_dpp v13, v13, v13 row_ror:8 row_mask:0xf bank_mask:0xf bound_ctrl:1
	v_add_f32_dpp v12, v12, v12 row_ror:4 row_mask:0xf bank_mask:0xf bound_ctrl:1
	v_add_f32_dpp v11, v11, v11 row_ror:2 row_mask:0xf bank_mask:0xf bound_ctrl:1
	v_add_f32_dpp v10, v10, v10 row_ror:1 row_mask:0xf bank_mask:0xf bound_ctrl:1
	v_add_f32_dpp v13, v13, v13 row_ror:4 row_mask:0xf bank_mask:0xf bound_ctrl:1
	v_add_f32_dpp v12, v12, v12 row_ror:2 row_mask:0xf bank_mask:0xf bound_ctrl:1
	v_add_f32_dpp v11, v11, v11 row_ror:1 row_mask:0xf bank_mask:0xf bound_ctrl:1
	v_sub_f32_e32 v10, v10, v122
	v_add_f32_dpp v13, v13, v13 row_ror:2 row_mask:0xf bank_mask:0xf bound_ctrl:1
	v_add_f32_dpp v12, v12, v12 row_ror:1 row_mask:0xf bank_mask:0xf bound_ctrl:1
	v_sub_f32_e32 v11, v11, v122
	v_exp_f32_e32 v10, v10
	v_add_f32_dpp v13, v13, v13 row_ror:1 row_mask:0xf bank_mask:0xf bound_ctrl:1
	v_sub_f32_e32 v14, v12, v122
	v_exp_f32_e32 v12, v11
	v_sub_f32_e32 v13, v13, v122
	v_exp_f32_e32 v14, v14
	v_exp_f32_e32 v16, v13
	v_add_f32_e32 v7, v7, v10
	v_pk_fma_f32 v[2:3], v[42:43], v[10:11], v[2:3] op_sel_hi:[1,0,1]
	v_pk_fma_f32 v[4:5], v[44:45], v[10:11], v[4:5] op_sel_hi:[1,0,1]
	v_add_f32_e32 v7, v7, v12
	v_pk_fma_f32 v[4:5], v[48:49], v[12:13], v[4:5] op_sel_hi:[1,0,1]
	v_pk_fma_f32 v[2:3], v[46:47], v[12:13], v[2:3] op_sel_hi:[1,0,1]
	v_add_f32_e32 v7, v7, v14
	v_pk_fma_f32 v[2:3], v[50:51], v[14:15], v[2:3] op_sel_hi:[1,0,1]
	v_pk_fma_f32 v[4:5], v[52:53], v[14:15], v[4:5] op_sel_hi:[1,0,1]
	v_add_f32_e32 v7, v7, v16
	v_pk_fma_f32 v[4:5], v[56:57], v[16:17], v[4:5] op_sel_hi:[1,0,1]
	v_pk_fma_f32 v[2:3], v[54:55], v[16:17], v[2:3] op_sel_hi:[1,0,1]
	v_mov_b32_e32 v210, v177
	v_mov_b32_e32 v177, v179
	v_mov_b32_e32 v211, v178
	v_mov_b32_e32 v178, v181
	v_mov_b32_e32 v181, v183
	v_pk_mul_f32 v[176:177], v[176:177], v[26:27]
	v_mov_b32_e32 v179, v182
	v_mov_b32_e32 v182, v185
	v_mov_b32_e32 v185, v187
	v_pk_mul_f32 v[180:181], v[180:181], v[26:27]
	v_pk_fma_f32 v[176:177], v[210:211], v[28:29], v[176:177]
; __device__ __forceinline__ float fast_exp2(float x) { return __builtin_amdgcn_exp2f(x); }
; #define AS_ROW(idx_, kv_, vv_) do { const int ix_ = (idx_); const bool fr_ = ix_ >= WIN;        \
;         const float* kp_ = fr_ ? nK + (size_t)(ix_ - WIN) * (HA * HD) : cK + (size_t)ix_ * (HA * HD); const float* vp_ = fr_ ? nV + (size_t)(ix_ - WIN) * (HA * HD) : cV + (size_t)ix_ * (HA * HD); \
;         kv_ = NTLD((const f32x4*)kp_); vv_ = NTLD((const f32x4*)vp_); } while (0)
; #define AS_DOT(kv_, q_) ({ float d_ = ((kv_)[0] * (q_)[0] + (kv_)[1] * (q_)[1]) + ((kv_)[2] * (q_)[2] + (kv_)[3] * (q_)[3]); \
;         d_ += AS_ROR(d_, 8); d_ += AS_ROR(d_, 4); d_ += AS_ROR(d_, 2); d_ += AS_ROR(d_, 1); d_; })
; __device__ __forceinline__ void attn_sample_item(Frame& F, int b, int h) {
;     ...
;             for (int u = 0; u < 4; ++u) { const float p = fast_exp2(AS_DOT(kv[u], qown) - mref); l16 += p; o16 += vv[u] * p; }
;         }
;         { f32x4 kv, vv; AS_ROW(WIN + w - 16 * 128, kv, vv); const float d = AS_DOT(kv, qown); const float p = g4 == 0 ? fast_exp2(d - mref) : 0.f; l16 += p; o16 += vv * p; }
;         AS_PUT(w, o16, l16);
	v_mov_b32_e32 v183, v186
	v_mov_b32_e32 v186, v191
	v_mov_b32_e32 v191, v193
	v_pk_mul_f32 v[184:185], v[184:185], v[26:27]
	v_pk_fma_f32 v[178:179], v[178:179], v[28:29], v[180:181]
	v_add_f32_e32 v176, v176, v177
	v_mov_b32_e32 v187, v192
	v_pk_mul_f32 v[190:191], v[190:191], v[26:27]
	v_pk_fma_f32 v[180:181], v[182:183], v[28:29], v[184:185]
	v_add_f32_e32 v177, v178, v179
	v_add_f32_dpp v176, v176, v176 row_ror:8 row_mask:0xf bank_mask:0xf bound_ctrl:1
	v_pk_fma_f32 v[182:183], v[186:187], v[28:29], v[190:191]
	v_add_f32_e32 v178, v180, v181
	v_add_f32_dpp v177, v177, v177 row_ror:8 row_mask:0xf bank_mask:0xf bound_ctrl:1
	v_add_f32_dpp v176, v176, v176 row_ror:4 row_mask:0xf bank_mask:0xf bound_ctrl:1
	v_add_f32_e32 v179, v182, v183
	v_add_f32_dpp v178, v178, v178 row_ror:8 row_mask:0xf bank_mask:0xf bound_ctrl:1
	v_add_f32_dpp v177, v177, v177 row_ror:4 row_mask:0xf bank_mask:0xf bound_ctrl:1
	v_add_f32_dpp v176, v176, v176 row_ror:2 row_mask:0xf bank_mask:0xf bound_ctrl:1
	v_add_f32_dpp v179, v179, v179 row_ror:8 row_mask:0xf bank_mask:0xf bound_ctrl:1
	v_add_f32_dpp v178, v178, v178 row_ror:4 row_mask:0xf bank_mask:0xf bound_ctrl:1
	v_add_f32_dpp v177, v177, v177 row_ror:2 row_mask:0xf bank_mask:0xf bound_ctrl:1
	v_add_f32_dpp v176, v176, v176 row_ror:1 row_mask:0xf bank_mask:0xf bound_ctrl:1
	v_add_f32_dpp v179, v179, v179 row_ror:4 row_mask:0xf bank_mask:0xf bound_ctrl:1
	v_add_f32_dpp v178, v178, v178 row_ror:2 row_mask:0xf bank_mask:0xf bound_ctrl:1
	v_add_f32_dpp v177, v177, v177 row_ror:1 row_mask:0xf bank_mask:0xf bound_ctrl:1
	v_sub_f32_e32 v176, v176, v122
	v_add_f32_dpp v179, v179, v179 row_ror:2 row_mask:0xf bank_mask:0xf bound_ctrl:1
	v_add_f32_dpp v178, v178, v178 row_ror:1 row_mask:0xf bank_mask:0xf bound_ctrl:1
	v_sub_f32_e32 v177, v177, v122
	v_exp_f32_e32 v176, v176
	v_add_f32_dpp v179, v179, v179 row_ror:1 row_mask:0xf bank_mask:0xf bound_ctrl:1
	v_sub_f32_e32 v180, v178, v122
	v_exp_f32_e32 v178, v177
	v_sub_f32_e32 v179, v179, v122
	v_exp_f32_e32 v180, v180
	v_exp_f32_e32 v182, v179
	v_add_f32_e32 v7, v7, v176
	v_pk_fma_f32 v[2:3], v[194:195], v[176:177], v[2:3] op_sel_hi:[1,0,1]
	v_pk_fma_f32 v[4:5], v[196:197], v[176:177], v[4:5] op_sel_hi:[1,0,1]
	v_add_f32_e32 v7, v7, v178
	v_pk_fma_f32 v[4:5], v[200:201], v[178:179], v[4:5] op_sel_hi:[1,0,1]
	v_pk_fma_f32 v[2:3], v[198:199], v[178:179], v[2:3] op_sel_hi:[1,0,1]
	v_add_f32_e32 v7, v7, v180
	v_pk_fma_f32 v[2:3], v[202:203], v[180:181], v[2:3] op_sel_hi:[1,0,1]
	v_pk_fma_f32 v[4:5], v[204:205], v[180:181], v[4:5] op_sel_hi:[1,0,1]
	v_add_f32_e32 v7, v7, v182
	v_pk_fma_f32 v[4:5], v[208:209], v[182:183], v[4:5] op_sel_hi:[1,0,1]
	v_pk_fma_f32 v[2:3], v[206:207], v[182:183], v[2:3] op_sel_hi:[1,0,1]
	s_cbranch_scc0 .LBB0_789
	s_add_i32 s8, s1, 0xfffff800
	s_cmpk_gt_i32 s1, 0x7ff
	s_cselect_b64 vcc, -1, 0
	s_and_b64 s[6:7], vcc, exec
	s_cselect_b32 s7, 0, s14
	s_cselect_b32 s6, s8, s1
	v_cndmask_b32_e32 v9, v33, v35, vcc
	v_cndmask_b32_e32 v8, v32, v34, vcc
	s_lshl_b64 s[6:7], s[6:7], 11
	v_lshl_add_u64 v[8:9], v[8:9], 0, s[6:7]
	flat_load_dwordx4 v[8:11], v[8:9] nt
	v_cndmask_b32_e32 v13, v31, v37, vcc
	v_cndmask_b32_e32 v12, v30, v36, vcc
	v_lshl_add_u64 v[12:13], v[12:13], 0, s[6:7]
	flat_load_dwordx4 v[12:15], v[12:13] nt
	v_cmp_lt_i32_e32 vcc, v119, v114
	v_cmp_eq_u32_e64 s[6:7], 0, v123
	s_mul_i32 s14, s1, 0x110
	s_waitcnt vmcnt(0) lgkmcnt(0)
	v_mov_b32_e32 v16, v9
	v_mov_b32_e32 v9, v11
	v_mov_b32_e32 v17, v10
	v_pk_mul_f32 v[8:9], v[8:9], v[26:27]
	s_nop 0
	v_pk_fma_f32 v[8:9], v[16:17], v[28:29], v[8:9]
	s_nop 0
	v_add_f32_e32 v6, v8, v9
	v_cndmask_b32_e32 v8, v25, v119, vcc
	v_lshlrev_b32_e32 v126, 2, v8
	v_add_f32_dpp v6, v6, v6 row_ror:8 row_mask:0xf bank_mask:0xf bound_ctrl:1
	v_cmp_lt_i32_e32 vcc, v120, v114
	s_nop 0
	v_add_f32_dpp v6, v6, v6 row_ror:4 row_mask:0xf bank_mask:0xf bound_ctrl:1
	s_nop 1
	v_add_f32_dpp v6, v6, v6 row_ror:2 row_mask:0xf bank_mask:0xf bound_ctrl:1
	s_nop 1
	v_add_f32_dpp v6, v6, v6 row_ror:1 row_mask:0xf bank_mask:0xf bound_ctrl:1
	v_sub_f32_e32 v6, v6, v122
	v_exp_f32_e32 v6, v6
	s_nop 0
	v_cndmask_b32_e64 v6, 0, v6, s[6:7]
	v_pk_fma_f32 v[4:5], v[14:15], v[6:7], v[4:5] op_sel_hi:[1,0,1]
	v_pk_fma_f32 v[2:3], v[12:13], v[6:7], v[2:3] op_sel_hi:[1,0,1]
	v_add_f32_e32 v10, v7, v6
	ds_bpermute_b32 v6, v126, v2
	ds_bpermute_b32 v7, v126, v3
	ds_bpermute_b32 v8, v126, v4
	ds_bpermute_b32 v9, v126, v5
	ds_bpermute_b32 v11, v126, v10
	v_cndmask_b32_e32 v12, v25, v120, vcc
	v_lshlrev_b32_e32 v127, 2, v12
	s_waitcnt lgkmcnt(3)
	v_pk_add_f32 v[2:3], v[2:3], v[6:7]
	s_waitcnt lgkmcnt(1)
	v_pk_add_f32 v[6:7], v[4:5], v[8:9]
	s_waitcnt lgkmcnt(0)
	v_add_f32_e32 v10, v10, v11
	ds_bpermute_b32 v4, v127, v2
	ds_bpermute_b32 v5, v127, v3
	ds_bpermute_b32 v8, v127, v6
	ds_bpermute_b32 v9, v127, v7
	ds_bpermute_b32 v11, v127, v10
	s_and_saveexec_b64 s[8:9], s[6:7]
	s_cbranch_execz .LBB0_793
	s_add_i32 s12, s14, 0
	s_waitcnt lgkmcnt(1)
	v_pk_add_f32 v[6:7], v[6:7], v[8:9]
	v_pk_add_f32 v[4:5], v[2:3], v[4:5]
	v_lshl_add_u32 v2, v24, 2, s12
	v_cmp_eq_u32_e32 vcc, 0, v121
	ds_write_b128 v2, v[4:7]
	s_and_b64 exec, exec, vcc
	s_cbranch_execz .LBB0_793
	s_waitcnt lgkmcnt(1)
	v_add_f32_e32 v2, v10, v11
	v_mov_b32_e32 v3, s12
	ds_write_b32 v3, v2 offset:256

; __device__ __forceinline__ float fast_exp2(float x) { return __builtin_amdgcn_exp2f(x); }
; #define AS_LDQ(tt) ({ const v2u r_ = *(const v2u*)(Qp + (row0 + (tt)) * DA + h * 64 + 4 * c); (f32x4){bflo(r_.x), bfhi(r_.x), bflo(r_.y), bfhi(r_.y)}; })
; #define AS_ROW(idx_, kv_, vv_) do { const int ix_ = (idx_); const bool fr_ = ix_ >= WIN;        \
;         const float* kp_ = fr_ ? nK + (size_t)(ix_ - WIN) * (HA * HD) : cK + (size_t)ix_ * (HA * HD); const float* vp_ = fr_ ? nV + (size_t)(ix_ - WIN) * (HA * HD) : cV + (size_t)ix_ * (HA * HD); \
;         kv_ = NTLD((const f32x4*)kp_); vv_ = NTLD((const f32x4*)vp_); } while (0)
; #define AS_DOT(kv_, q_) ({ float d_ = ((kv_)[0] * (q_)[0] + (kv_)[1] * (q_)[1]) + ((kv_)[2] * (q_)[2] + (kv_)[3] * (q_)[3]); \
;         d_ += AS_ROR(d_, 8); d_ += AS_ROR(d_, 4); d_ += AS_ROR(d_, 2); d_ += AS_ROR(d_, 1); d_; })
; __device__ __forceinline__ void attn_sample_item(Frame& F, int b, int h) {
;     ...
;     if (w < 4) {
;         const f32x4 q4a = AS_LDQ(w), q4b = AS_LDQ(w + 4);
;         f32x4 o4a = {0.f, 0.f, 0.f, 0.f}, o4b = {0.f, 0.f, 0.f, 0.f}; float l4a = 0.f, l4b = 0.f;
; #pragma unroll 1
;         for (int it0 = 0; it0 < 32; it0 += 4) {
;             f32x4 kv[4], vv[4];
; #pragma unroll
;             for (int u = 0; u < 4; ++u) AS_ROW(WIN + w + 4 - 4 * (4 * (it0 + u) + g4), kv[u], vv[u]);
; #pragma unroll
;             for (int u = 0; u < 4; ++u) {
;                 const int m = 4 * (it0 + u) + g4;
;                 const float da = AS_DOT(kv[u], q4a), db = AS_DOT(kv[u], q4b);
;                 const float pa = m >= 1 ? fast_exp2(da - mref) : 0.f, pb = fast_exp2(db - mref);
;                 l4a += pa; o4a += vv[u] * pa; l4b += pb; o4b += vv[u] * pb;
;             }
.LBB0_837:
	s_and_b64 vcc, exec, s[8:9]
	s_cbranch_vccz .LBB0_847
	s_add_i32 s8, s1, 4
	s_ashr_i32 s9, s8, 31
	s_add_u32 s8, s42, s8
	s_addc_u32 s9, s43, s9
	s_lshl_b64 s[8:9], s[8:9], 10
	s_add_u32 s8, s53, s8
	s_addc_u32 s9, s54, s9
	s_lshl_b32 s12, s0, 1
	s_add_u32 s8, s8, s12
	s_addc_u32 s9, s9, 0
	s_waitcnt lgkmcnt(3)
	global_load_dwordx2 v[4:5], v38, s[8:9]
	v_mov_b32_e32 v14, 0
	s_mov_b32 s8, -4
	v_mad_i32_i24 v2, v123, -4, s1
	s_mov_b32 s9, 0
	v_mov_b32_e32 v15, v14
	v_mov_b32_e32 v18, v14
	v_mov_b32_e32 v19, v14
	s_waitcnt lgkmcnt(2)
	v_mov_b32_e32 v8, v14
	s_waitcnt lgkmcnt(1)
	v_mov_b32_e32 v9, v14
	v_mov_b32_e32 v6, v14
	v_mov_b32_e32 v7, v14
	v_mov_b32_e32 v10, v14
	s_waitcnt lgkmcnt(0)
	v_mov_b32_e32 v11, v14
	s_waitcnt vmcnt(0)
	v_lshlrev_b32_e32 v16, 16, v4
	v_and_b32_e32 v17, 0xffff0000, v5
	v_and_b32_e32 v12, 0xffff0000, v4
	v_lshlrev_b32_e32 v13, 16, v5
	v_cmp_eq_u32_e32 vcc, 1, v123
	s_nop 1
	v_cndmask_b32_e64 v172, 0, 1.0, vcc
	v_sub_f32_e32 v172, v122, v172
	v_cmp_eq_u32_e32 vcc, 0, v123
	s_nop 1
	v_cndmask_b32_e64 v173, 0, 1.0, vcc
	v_sub_f32_e32 v173, v122, v173
.LBB0_839:
	v_add_u32_e32 v3, s9, v2
	v_add_u32_e32 v22, 0x804, v3
	v_add_u32_e32 v4, 0x7f4, v3
	v_add_u32_e32 v20, 0x7e4, v3
	v_add_u32_e32 v39, 4, v3
	v_add_u32_e32 v40, 0x7d4, v3
	v_ashrrev_i32_e32 v3, 31, v22
	v_ashrrev_i32_e32 v5, 31, v4
	v_ashrrev_i32_e32 v21, 31, v20
	v_cmp_lt_i32_e32 vcc, s72, v22
	v_ashrrev_i32_e32 v41, 31, v40
	v_lshlrev_b64 v[4:5], 11, v[4:5]
	v_cndmask_b32_e64 v43, v3, 0, vcc
	v_cndmask_b32_e32 v42, v22, v39, vcc
	v_lshlrev_b64 v[20:21], 11, v[20:21]
	v_cndmask_b32_e32 v45, v33, v35, vcc
	v_cndmask_b32_e32 v44, v32, v34, vcc
	v_cndmask_b32_e32 v49, v31, v37, vcc
	v_cndmask_b32_e32 v48, v30, v36, vcc
	v_lshlrev_b64 v[40:41], 11, v[40:41]
	v_lshlrev_b64 v[50:51], 11, v[42:43]
	v_lshl_add_u64 v[42:43], v[32:33], 0, v[4:5]
	v_lshl_add_u64 v[46:47], v[32:33], 0, v[20:21]
	v_lshl_add_u64 v[4:5], v[30:31], 0, v[4:5]
	v_lshl_add_u64 v[52:53], v[32:33], 0, v[40:41]
	v_lshl_add_u64 v[60:61], v[30:31], 0, v[40:41]
	global_load_dwordx4 v[40:43], v[42:43], off nt
	v_lshl_add_u64 v[64:65], v[44:45], 0, v[50:51]
	global_load_dwordx4 v[44:47], v[46:47], off nt
	v_lshl_add_u64 v[68:69], v[48:49], 0, v[50:51]
	v_lshl_add_u64 v[20:21], v[30:31], 0, v[20:21]
	global_load_dwordx4 v[48:51], v[4:5], off nt
	s_nop 0
	global_load_dwordx4 v[52:55], v[52:53], off nt
	s_nop 0
	global_load_dwordx4 v[56:59], v[20:21], off nt
	s_nop 0
	global_load_dwordx4 v[60:63], v[60:61], off nt
	s_nop 0
	global_load_dwordx4 v[64:67], v[64:65], off nt
	s_nop 0
	global_load_dwordx4 v[68:71], v[68:69], off nt
	v_cmp_ne_u32_e64 s[98:99], s9, v125
	s_add_i32 s8, s8, 4
	s_sub_i32 s9, s9, 64
	v_add_u32_e32 v177, s9, v2
	v_add_u32_e32 v182, 0x804, v177
	v_add_u32_e32 v178, 0x7f4, v177
	v_add_u32_e32 v180, 0x7e4, v177
	v_add_u32_e32 v185, 4, v177
	v_add_u32_e32 v186, 0x7d4, v177
	v_ashrrev_i32_e32 v177, 31, v182
	v_ashrrev_i32_e32 v179, 31, v178
	v_ashrrev_i32_e32 v181, 31, v180
	v_cmp_lt_i32_e32 vcc, s72, v182
	v_ashrrev_i32_e32 v187, 31, v186
	v_lshlrev_b64 v[178:179], 11, v[178:179]
	v_cndmask_b32_e64 v189, v177, 0, vcc
	v_cndmask_b32_e32 v188, v182, v185, vcc
	v_lshlrev_b64 v[180:181], 11, v[180:181]
	v_cndmask_b32_e32 v191, v33, v35, vcc
	v_cndmask_b32_e32 v190, v32, v34, vcc
	v_cndmask_b32_e32 v195, v31, v37, vcc
	v_cndmask_b32_e32 v194, v30, v36, vcc
	v_lshlrev_b64 v[186:187], 11, v[186:187]
	v_lshlrev_b64 v[196:197], 11, v[188:189]
	v_lshl_add_u64 v[188:189], v[32:33], 0, v[178:179]
	v_lshl_add_u64 v[192:193], v[32:33], 0, v[180:181]
	v_lshl_add_u64 v[178:179], v[30:31], 0, v[178:179]
	v_lshl_add_u64 v[198:199], v[32:33], 0, v[186:187]
	v_lshl_add_u64 v[206:207], v[30:31], 0, v[186:187]
	global_load_dwordx4 v[186:189], v[188:189], off nt
	v_lshl_add_u64 v[210:211], v[190:191], 0, v[196:197]
	global_load_dwordx4 v[190:193], v[192:193], off nt
	v_lshl_add_u64 v[214:215], v[194:195], 0, v[196:197]
	v_lshl_add_u64 v[180:181], v[30:31], 0, v[180:181]
	global_load_dwordx4 v[194:197], v[178:179], off nt
	s_nop 0
	global_load_dwordx4 v[198:201], v[198:199], off nt
	s_nop 0
	global_load_dwordx4 v[202:205], v[180:181], off nt
	s_nop 0
	global_load_dwordx4 v[206:209], v[206:207], off nt
	s_nop 0
	global_load_dwordx4 v[210:213], v[210:211], off nt
	s_nop 0
	global_load_dwordx4 v[214:217], v[214:215], off nt
	v_cmp_ne_u32_e32 vcc, s9, v125
	s_add_i32 s8, s8, 4
	s_sub_i32 s9, s9, 64
	s_cmp_gt_u32 s8, 27
	s_waitcnt vmcnt(0)
; __device__ __forceinline__ float fast_exp2(float x) { return __builtin_amdgcn_exp2f(x); }
; #define AS_DOT(kv_, q_) ({ float d_ = ((kv_)[0] * (q_)[0] + (kv_)[1] * (q_)[1]) + ((kv_)[2] * (q_)[2] + (kv_)[3] * (q_)[3]); \
;         d_ += AS_ROR(d_, 8); d_ += AS_ROR(d_, 4); d_ += AS_ROR(d_, 2); d_ += AS_ROR(d_, 1); d_; })
; __device__ __forceinline__ void attn_sample_item(Frame& F, int b, int h) {
;     ...
;             for (int u = 0; u < 4; ++u) {
;                 const int m = 4 * (it0 + u) + g4;
;                 const float da = AS_DOT(kv[u], q4a), db = AS_DOT(kv[u], q4b);
;                 const float pa = m >= 1 ? fast_exp2(da - mref) : 0.f, pb = fast_exp2(db - mref);
;                 l4a += pa; o4a += vv[u] * pa; l4b += pb; o4b += vv[u] * pb;
;             }
	v_mov_b32_e32 v4, v41
	v_mov_b32_e32 v5, v42
	v_mov_b32_e32 v41, v43
	v_mov_b32_e32 v20, v45
	v_mov_b32_e32 v21, v46
	v_mov_b32_e32 v45, v47
	v_mov_b32_e32 v42, v53
	v_mov_b32_e32 v53, v55
	v_mov_b32_e32 v46, v65
	v_mov_b32_e32 v65, v67
	v_mov_b32_e32 v43, v54
	v_mov_b32_e32 v47, v66
	v_pk_mul_f32 v[54:55], v[40:41], v[26:27]
	v_pk_mul_f32 v[40:41], v[40:41], v[16:17]
	v_pk_mul_f32 v[66:67], v[44:45], v[26:27]
	v_pk_mul_f32 v[44:45], v[44:45], v[16:17]
	v_pk_mul_f32 v[72:73], v[52:53], v[26:27]
	v_pk_mul_f32 v[52:53], v[52:53], v[16:17]
	v_pk_mul_f32 v[74:75], v[64:65], v[26:27]
	v_pk_mul_f32 v[64:65], v[64:65], v[16:17]
	v_pk_fma_f32 v[54:55], v[4:5], v[28:29], v[54:55]
	v_pk_fma_f32 v[4:5], v[4:5], v[12:13], v[40:41]
	v_pk_fma_f32 v[40:41], v[20:21], v[28:29], v[66:67]
	v_pk_fma_f32 v[20:21], v[20:21], v[12:13], v[44:45]
	v_pk_fma_f32 v[44:45], v[42:43], v[28:29], v[72:73]
	v_pk_fma_f32 v[42:43], v[42:43], v[12:13], v[52:53]
	v_pk_fma_f32 v[52:53], v[46:47], v[28:29], v[74:75]
	v_pk_fma_f32 v[46:47], v[46:47], v[12:13], v[64:65]
	v_add_f32_e32 v3, v54, v55
	v_add_f32_e32 v39, v52, v53
	v_add_f32_e32 v4, v4, v5
	v_add_f32_e32 v5, v40, v41
	v_add_f32_e32 v22, v42, v43
	v_add_f32_e32 v40, v46, v47
	v_add_f32_dpp v3, v3, v3 row_ror:8 row_mask:0xf bank_mask:0xf bound_ctrl:1
	v_add_f32_dpp v39, v39, v39 row_ror:8 row_mask:0xf bank_mask:0xf bound_ctrl:1
	v_add_f32_dpp v4, v4, v4 row_ror:8 row_mask:0xf bank_mask:0xf bound_ctrl:1
	v_add_f32_dpp v22, v22, v22 row_ror:8 row_mask:0xf bank_mask:0xf bound_ctrl:1
	v_add_f32_dpp v40, v40, v40 row_ror:8 row_mask:0xf bank_mask:0xf bound_ctrl:1
	v_add_f32_dpp v3, v3, v3 row_ror:4 row_mask:0xf bank_mask:0xf bound_ctrl:1
	v_add_f32_dpp v39, v39, v39 row_ror:4 row_mask:0xf bank_mask:0xf bound_ctrl:1
	v_add_f32_e32 v20, v20, v21
	v_add_f32_dpp v4, v4, v4 row_ror:4 row_mask:0xf bank_mask:0xf bound_ctrl:1
	v_add_f32_dpp v22, v22, v22 row_ror:4 row_mask:0xf bank_mask:0xf bound_ctrl:1
	v_add_f32_dpp v40, v40, v40 row_ror:4 row_mask:0xf bank_mask:0xf bound_ctrl:1
	v_add_f32_dpp v3, v3, v3 row_ror:2 row_mask:0xf bank_mask:0xf bound_ctrl:1
	v_add_f32_dpp v39, v39, v39 row_ror:2 row_mask:0xf bank_mask:0xf bound_ctrl:1
	v_add_f32_dpp v20, v20, v20 row_ror:8 row_mask:0xf bank_mask:0xf bound_ctrl:1
	v_add_f32_dpp v4, v4, v4 row_ror:2 row_mask:0xf bank_mask:0xf bound_ctrl:1
	v_add_f32_dpp v22, v22, v22 row_ror:2 row_mask:0xf bank_mask:0xf bound_ctrl:1
	v_add_f32_dpp v40, v40, v40 row_ror:2 row_mask:0xf bank_mask:0xf bound_ctrl:1
	v_add_f32_dpp v3, v3, v3 row_ror:1 row_mask:0xf bank_mask:0xf bound_ctrl:1
	v_add_f32_dpp v39, v39, v39 row_ror:1 row_mask:0xf bank_mask:0xf bound_ctrl:1
	v_add_f32_e32 v21, v44, v45
	v_add_f32_dpp v5, v5, v5 row_ror:8 row_mask:0xf bank_mask:0xf bound_ctrl:1
	v_add_f32_dpp v20, v20, v20 row_ror:4 row_mask:0xf bank_mask:0xf bound_ctrl:1
	v_add_f32_dpp v4, v4, v4 row_ror:1 row_mask:0xf bank_mask:0xf bound_ctrl:1
	v_add_f32_dpp v22, v22, v22 row_ror:1 row_mask:0xf bank_mask:0xf bound_ctrl:1
	v_add_f32_dpp v40, v40, v40 row_ror:1 row_mask:0xf bank_mask:0xf bound_ctrl:1
	v_sub_f32_e32 v3, v3, v172
	v_sub_f32_e32 v39, v39, v172
	v_add_f32_dpp v21, v21, v21 row_ror:8 row_mask:0xf bank_mask:0xf bound_ctrl:1
	v_add_f32_dpp v5, v5, v5 row_ror:4 row_mask:0xf bank_mask:0xf bound_ctrl:1
	v_add_f32_dpp v20, v20, v20 row_ror:2 row_mask:0xf bank_mask:0xf bound_ctrl:1
	v_sub_f32_e32 v41, v4, v173
	v_sub_f32_e32 v22, v22, v173
	v_sub_f32_e32 v44, v40, v173
	v_exp_f32_e32 v4, v3
	v_exp_f32_e32 v3, v39
	v_add_f32_dpp v21, v21, v21 row_ror:4 row_mask:0xf bank_mask:0xf bound_ctrl:1
	v_add_f32_dpp v5, v5, v5 row_ror:2 row_mask:0xf bank_mask:0xf bound_ctrl:1
	v_add_f32_dpp v20, v20, v20 row_ror:1 row_mask:0xf bank_mask:0xf bound_ctrl:1
	v_exp_f32_e32 v43, v22
	v_exp_f32_e32 v22, v44
	v_add_f32_dpp v21, v21, v21 row_ror:2 row_mask:0xf bank_mask:0xf bound_ctrl:1
	v_add_f32_dpp v5, v5, v5 row_ror:1 row_mask:0xf bank_mask:0xf bound_ctrl:1
	v_sub_f32_e32 v42, v20, v173
	v_exp_f32_e32 v20, v41
	v_add_f32_dpp v21, v21, v21 row_ror:1 row_mask:0xf bank_mask:0xf bound_ctrl:1
	v_sub_f32_e32 v5, v5, v172
	v_exp_f32_e32 v41, v42
	v_sub_f32_e32 v21, v21, v172
	v_exp_f32_e32 v40, v5
	v_cndmask_b32_e64 v52, 0, v3, s[98:99]
	v_exp_f32_e32 v42, v21
	v_pk_fma_f32 v[14:15], v[68:69], v[52:53], v[14:15] op_sel_hi:[1,0,1]
	v_pk_fma_f32 v[18:19], v[70:71], v[52:53], v[18:19] op_sel_hi:[1,0,1]
	v_mov_b32_e32 v53, v22
	v_pk_fma_f32 v[8:9], v[68:69], v[22:23], v[8:9] op_sel_hi:[1,0,1]
	v_pk_fma_f32 v[6:7], v[70:71], v[22:23], v[6:7] op_sel_hi:[1,0,1]
	v_pk_fma_f32 v[18:19], v[50:51], v[4:5], v[18:19] op_sel_hi:[1,0,1]
	v_pk_fma_f32 v[14:15], v[48:49], v[4:5], v[14:15] op_sel_hi:[1,0,1]
	v_pk_add_f32 v[10:11], v[10:11], v[52:53]
	v_mov_b32_e32 v5, v20
	v_mov_b32_e32 v44, v41
	v_pk_fma_f32 v[6:7], v[50:51], v[20:21], v[6:7] op_sel_hi:[1,0,1]
	v_pk_fma_f32 v[8:9], v[48:49], v[20:21], v[8:9] op_sel_hi:[1,0,1]
	v_pk_add_f32 v[4:5], v[10:11], v[4:5]
	v_mov_b32_e32 v46, v43
	v_pk_fma_f32 v[8:9], v[56:57], v[44:45], v[8:9] op_sel_hi:[1,0,1]
	v_pk_fma_f32 v[6:7], v[58:59], v[44:45], v[6:7] op_sel_hi:[1,0,1]
	v_pk_fma_f32 v[14:15], v[56:57], v[40:41], v[14:15] op_sel_hi:[1,0,1]
	v_pk_fma_f32 v[18:19], v[58:59], v[40:41], v[18:19] op_sel_hi:[1,0,1]
	v_pk_add_f32 v[4:5], v[4:5], v[40:41]
	v_pk_fma_f32 v[6:7], v[62:63], v[46:47], v[6:7] op_sel_hi:[1,0,1]
	v_pk_fma_f32 v[8:9], v[60:61], v[46:47], v[8:9] op_sel_hi:[1,0,1]
	v_pk_fma_f32 v[18:19], v[62:63], v[42:43], v[18:19] op_sel_hi:[1,0,1]
	v_pk_fma_f32 v[14:15], v[60:61], v[42:43], v[14:15] op_sel_hi:[1,0,1]
	v_pk_add_f32 v[10:11], v[4:5], v[42:43]
	v_mov_b32_e32 v178, v187
	v_mov_b32_e32 v179, v188
; __device__ __forceinline__ float fast_exp2(float x) { return __builtin_amdgcn_exp2f(x); }
; #define AS_DOT(kv_, q_) ({ float d_ = ((kv_)[0] * (q_)[0] + (kv_)[1] * (q_)[1]) + ((kv_)[2] * (q_)[2] + (kv_)[3] * (q_)[3]); \
;         d_ += AS_ROR(d_, 8); d_ += AS_ROR(d_, 4); d_ += AS_ROR(d_, 2); d_ += AS_ROR(d_, 1); d_; })
; __device__ __forceinline__ void attn_sample_item(Frame& F, int b, int h) {
;     ...
;             for (int u = 0; u < 4; ++u) {
;                 const int m = 4 * (it0 + u) + g4;
;                 const float da = AS_DOT(kv[u], q4a), db = AS_DOT(kv[u], q4b);
;                 const float pa = m >= 1 ? fast_exp2(da - mref) : 0.f, pb = fast_exp2(db - mref);
;                 l4a += pa; o4a += vv[u] * pa; l4b += pb; o4b += vv[u] * pb;
;             }
	v_mov_b32_e32 v187, v189
	v_mov_b32_e32 v180, v191
	v_mov_b32_e32 v181, v192
	v_mov_b32_e32 v191, v193
	v_mov_b32_e32 v188, v199
	v_mov_b32_e32 v199, v201
	v_mov_b32_e32 v192, v211
	v_mov_b32_e32 v211, v213
	v_mov_b32_e32 v189, v200
	v_mov_b32_e32 v193, v212
	v_pk_mul_f32 v[200:201], v[186:187], v[26:27]
	v_pk_mul_f32 v[186:187], v[186:187], v[16:17]
	v_pk_mul_f32 v[212:213], v[190:191], v[26:27]
	v_pk_mul_f32 v[190:191], v[190:191], v[16:17]
	v_pk_mul_f32 v[218:219], v[198:199], v[26:27]
	v_pk_mul_f32 v[198:199], v[198:199], v[16:17]
	v_pk_mul_f32 v[220:221], v[210:211], v[26:27]
	v_pk_mul_f32 v[210:211], v[210:211], v[16:17]
	v_pk_fma_f32 v[200:201], v[178:179], v[28:29], v[200:201]
	v_pk_fma_f32 v[178:179], v[178:179], v[12:13], v[186:187]
	v_pk_fma_f32 v[186:187], v[180:181], v[28:29], v[212:213]
	v_pk_fma_f32 v[180:181], v[180:181], v[12:13], v[190:191]
	v_pk_fma_f32 v[190:191], v[188:189], v[28:29], v[218:219]
	v_pk_fma_f32 v[188:189], v[188:189], v[12:13], v[198:199]
	v_pk_fma_f32 v[198:199], v[192:193], v[28:29], v[220:221]
	v_pk_fma_f32 v[192:193], v[192:193], v[12:13], v[210:211]
	v_add_f32_e32 v177, v200, v201
	v_add_f32_e32 v185, v198, v199
	v_add_f32_e32 v178, v178, v179
	v_add_f32_e32 v179, v186, v187
	v_add_f32_e32 v182, v188, v189
	v_add_f32_e32 v186, v192, v193
	v_add_f32_dpp v177, v177, v177 row_ror:8 row_mask:0xf bank_mask:0xf bound_ctrl:1
	v_add_f32_dpp v185, v185, v185 row_ror:8 row_mask:0xf bank_mask:0xf bound_ctrl:1
	v_add_f32_dpp v178, v178, v178 row_ror:8 row_mask:0xf bank_mask:0xf bound_ctrl:1
	v_add_f32_dpp v182, v182, v182 row_ror:8 row_mask:0xf bank_mask:0xf bound_ctrl:1
	v_add_f32_dpp v186, v186, v186 row_ror:8 row_mask:0xf bank_mask:0xf bound_ctrl:1
	v_add_f32_dpp v177, v177, v177 row_ror:4 row_mask:0xf bank_mask:0xf bound_ctrl:1
	v_add_f32_dpp v185, v185, v185 row_ror:4 row_mask:0xf bank_mask:0xf bound_ctrl:1
	v_add_f32_e32 v180, v180, v181
	v_add_f32_dpp v178, v178, v178 row_ror:4 row_mask:0xf bank_mask:0xf bound_ctrl:1
	v_add_f32_dpp v182, v182, v182 row_ror:4 row_mask:0xf bank_mask:0xf bound_ctrl:1
	v_add_f32_dpp v186, v186, v186 row_ror:4 row_mask:0xf bank_mask:0xf bound_ctrl:1
	v_add_f32_dpp v177, v177, v177 row_ror:2 row_mask:0xf bank_mask:0xf bound_ctrl:1
	v_add_f32_dpp v185, v185, v185 row_ror:2 row_mask:0xf bank_mask:0xf bound_ctrl:1
	v_add_f32_dpp v180, v180, v180 row_ror:8 row_mask:0xf bank_mask:0xf bound_ctrl:1
	v_add_f32_dpp v178, v178, v178 row_ror:2 row_mask:0xf bank_mask:0xf bound_ctrl:1
	v_add_f32_dpp v182, v182, v182 row_ror:2 row_mask:0xf bank_mask:0xf bound_ctrl:1
	v_add_f32_dpp v186, v186, v186 row_ror:2 row_mask:0xf bank_mask:0xf bound_ctrl:1
	v_add_f32_dpp v177, v177, v177 row_ror:1 row_mask:0xf bank_mask:0xf bound_ctrl:1
	v_add_f32_dpp v185, v185, v185 row_ror:1 row_mask:0xf bank_mask:0xf bound_ctrl:1
	v_add_f32_e32 v181, v190, v191
	v_add_f32_dpp v179, v179, v179 row_ror:8 row_mask:0xf bank_mask:0xf bound_ctrl:1
	v_add_f32_dpp v180, v180, v180 row_ror:4 row_mask:0xf bank_mask:0xf bound_ctrl:1
	v_add_f32_dpp v178, v178, v178 row_ror:1 row_mask:0xf bank_mask:0xf bound_ctrl:1
	v_add_f32_dpp v182, v182, v182 row_ror:1 row_mask:0xf bank_mask:0xf bound_ctrl:1
	v_add_f32_dpp v186, v186, v186 row_ror:1 row_mask:0xf bank_mask:0xf bound_ctrl:1
	v_sub_f32_e32 v177, v177, v172
	v_sub_f32_e32 v185, v185, v172
	v_add_f32_dpp v181, v181, v181 row_ror:8 row_mask:0xf bank_mask:0xf bound_ctrl:1
	v_add_f32_dpp v179, v179, v179 row_ror:4 row_mask:0xf bank_mask:0xf bound_ctrl:1
	v_add_f32_dpp v180, v180, v180 row_ror:2 row_mask:0xf bank_mask:0xf bound_ctrl:1
	v_sub_f32_e32 v187, v178, v173
	v_sub_f32_e32 v182, v182, v173
	v_sub_f32_e32 v190, v186, v173
	v_exp_f32_e32 v178, v177
	v_exp_f32_e32 v177, v185
	v_add_f32_dpp v181, v181, v181 row_ror:4 row_mask:0xf bank_mask:0xf bound_ctrl:1
	v_add_f32_dpp v179, v179, v179 row_ror:2 row_mask:0xf bank_mask:0xf bound_ctrl:1
	v_add_f32_dpp v180, v180, v180 row_ror:1 row_mask:0xf bank_mask:0xf bound_ctrl:1
	v_exp_f32_e32 v189, v182
	v_exp_f32_e32 v182, v190
	v_add_f32_dpp v181, v181, v181 row_ror:2 row_mask:0xf bank_mask:0xf bound_ctrl:1
	v_add_f32_dpp v179, v179, v179 row_ror:1 row_mask:0xf bank_mask:0xf bound_ctrl:1
	v_sub_f32_e32 v188, v180, v173
	v_exp_f32_e32 v180, v187
	v_add_f32_dpp v181, v181, v181 row_ror:1 row_mask:0xf bank_mask:0xf bound_ctrl:1
	v_sub_f32_e32 v179, v179, v172
	v_exp_f32_e32 v187, v188
	v_sub_f32_e32 v181, v181, v172
	v_exp_f32_e32 v186, v179
	v_cndmask_b32_e32 v198, 0, v177, vcc
	v_exp_f32_e32 v188, v181
	v_pk_fma_f32 v[14:15], v[214:215], v[198:199], v[14:15] op_sel_hi:[1,0,1]
	v_pk_fma_f32 v[18:19], v[216:217], v[198:199], v[18:19] op_sel_hi:[1,0,1]
	v_mov_b32_e32 v199, v182
	v_pk_fma_f32 v[8:9], v[214:215], v[182:183], v[8:9] op_sel_hi:[1,0,1]
	v_pk_fma_f32 v[6:7], v[216:217], v[182:183], v[6:7] op_sel_hi:[1,0,1]
	v_pk_fma_f32 v[18:19], v[196:197], v[178:179], v[18:19] op_sel_hi:[1,0,1]
	v_pk_fma_f32 v[14:15], v[194:195], v[178:179], v[14:15] op_sel_hi:[1,0,1]
	v_pk_add_f32 v[10:11], v[10:11], v[198:199]
	v_mov_b32_e32 v179, v180
	v_mov_b32_e32 v190, v187
	v_pk_fma_f32 v[6:7], v[196:197], v[180:181], v[6:7] op_sel_hi:[1,0,1]
	v_pk_fma_f32 v[8:9], v[194:195], v[180:181], v[8:9] op_sel_hi:[1,0,1]
	v_pk_add_f32 v[178:179], v[10:11], v[178:179]
	v_mov_b32_e32 v192, v189
	v_pk_fma_f32 v[8:9], v[202:203], v[190:191], v[8:9] op_sel_hi:[1,0,1]
	v_pk_fma_f32 v[6:7], v[204:205], v[190:191], v[6:7] op_sel_hi:[1,0,1]
	v_pk_fma_f32 v[14:15], v[202:203], v[186:187], v[14:15] op_sel_hi:[1,0,1]
	v_pk_fma_f32 v[18:19], v[204:205], v[186:187], v[18:19] op_sel_hi:[1,0,1]
	v_pk_add_f32 v[178:179], v[178:179], v[186:187]
	v_pk_fma_f32 v[6:7], v[208:209], v[192:193], v[6:7] op_sel_hi:[1,0,1]
	v_pk_fma_f32 v[8:9], v[206:207], v[192:193], v[8:9] op_sel_hi:[1,0,1]
	v_pk_fma_f32 v[18:19], v[208:209], v[188:189], v[18:19] op_sel_hi:[1,0,1]
	v_pk_fma_f32 v[14:15], v[206:207], v[188:189], v[14:15] op_sel_hi:[1,0,1]
	v_pk_add_f32 v[10:11], v[178:179], v[188:189]
	s_cbranch_scc0 .LBB0_839
; __device__ __forceinline__ float fast_exp2(float x) { return __builtin_amdgcn_exp2f(x); }
; #define AS_ROW(idx_, kv_, vv_) do { const int ix_ = (idx_); const bool fr_ = ix_ >= WIN;        \
;         const float* kp_ = fr_ ? nK + (size_t)(ix_ - WIN) * (HA * HD) : cK + (size_t)ix_ * (HA * HD); const float* vp_ = fr_ ? nV + (size_t)(ix_ - WIN) * (HA * HD) : cV + (size_t)ix_ * (HA * HD); \
;         kv_ = NTLD((const f32x4*)kp_); vv_ = NTLD((const f32x4*)vp_); } while (0)
; #define AS_DOT(kv_, q_) ({ float d_ = ((kv_)[0] * (q_)[0] + (kv_)[1] * (q_)[1]) + ((kv_)[2] * (q_)[2] + (kv_)[3] * (q_)[3]); \
;         d_ += AS_ROR(d_, 8); d_ += AS_ROR(d_, 4); d_ += AS_ROR(d_, 2); d_ += AS_ROR(d_, 1); d_; })
; __device__ __forceinline__ void attn_sample_item(Frame& F, int b, int h) {
;     ...
;         { const int m = 128 + (g4 & 1); f32x4 kv, vv; AS_ROW(WIN + w + 4 - 4 * m, kv, vv);
;           const float da = AS_DOT(kv, q4a), db = AS_DOT(kv, q4b);
;           const float pa = g4 < 2 ? fast_exp2(da - mref) : 0.f, pb = g4 == 0 ? fast_exp2(db - mref) : 0.f;
;           l4a += pa; o4a += vv * pa; l4b += pb; o4b += vv * pb; }
;         AS_PUT(8 + w, o4a, l4a); AS_PUT(12 + w, o4b, l4b);
	v_lshlrev_b32_e32 v2, 2, v124
	v_and_b32_e32 v2, 4, v2
	v_sub_u32_e32 v2, s1, v2
	v_add_u32_e32 v2, 0x604, v2
	v_ashrrev_i32_e32 v3, 31, v2
	v_lshlrev_b64 v[2:3], 11, v[2:3]
	v_lshl_add_u64 v[4:5], v[32:33], 0, v[2:3]
	flat_load_dwordx4 v[32:35], v[4:5] nt
	v_lshl_add_u64 v[2:3], v[30:31], 0, v[2:3]
	flat_load_dwordx4 v[2:5], v[2:3] nt
	v_cmp_gt_u32_e32 vcc, 2, v123
	s_waitcnt vmcnt(0) lgkmcnt(0)
	v_mov_b32_e32 v20, v33
	v_mov_b32_e32 v33, v35
	v_mov_b32_e32 v21, v34
	v_pk_mul_f32 v[26:27], v[32:33], v[26:27]
	v_pk_mul_f32 v[16:17], v[32:33], v[16:17]
	v_pk_fma_f32 v[26:27], v[20:21], v[28:29], v[26:27]
	v_pk_fma_f32 v[12:13], v[20:21], v[12:13], v[16:17]
	v_add_f32_e32 v22, v26, v27
	v_add_f32_e32 v20, v12, v13
	s_nop 0
	v_add_f32_dpp v22, v22, v22 row_ror:8 row_mask:0xf bank_mask:0xf bound_ctrl:1
	v_add_f32_dpp v20, v20, v20 row_ror:8 row_mask:0xf bank_mask:0xf bound_ctrl:1
	s_nop 0
	v_add_f32_dpp v22, v22, v22 row_ror:4 row_mask:0xf bank_mask:0xf bound_ctrl:1
	v_add_f32_dpp v20, v20, v20 row_ror:4 row_mask:0xf bank_mask:0xf bound_ctrl:1
	s_nop 0
	v_add_f32_dpp v22, v22, v22 row_ror:2 row_mask:0xf bank_mask:0xf bound_ctrl:1
	v_add_f32_dpp v20, v20, v20 row_ror:2 row_mask:0xf bank_mask:0xf bound_ctrl:1
	s_nop 0
	v_add_f32_dpp v22, v22, v22 row_ror:1 row_mask:0xf bank_mask:0xf bound_ctrl:1
	v_sub_f32_e32 v22, v22, v122
	v_exp_f32_e32 v22, v22
	v_mov_b32_dpp v21, v20 row_ror:1 row_mask:0xf bank_mask:0xf bound_ctrl:1
	v_cndmask_b32_e32 v22, 0, v22, vcc
	v_pk_fma_f32 v[18:19], v[4:5], v[22:23], v[18:19] op_sel_hi:[1,0,1]
	v_pk_fma_f32 v[14:15], v[2:3], v[22:23], v[14:15] op_sel_hi:[1,0,1]
	v_add_f32_e32 v10, v10, v22
	ds_bpermute_b32 v26, v126, v14
	ds_bpermute_b32 v27, v126, v15
	ds_bpermute_b32 v28, v126, v18
	ds_bpermute_b32 v29, v126, v19
	ds_bpermute_b32 v22, v126, v10
	s_waitcnt lgkmcnt(3)
	v_pk_add_f32 v[12:13], v[14:15], v[26:27]
	ds_bpermute_b32 v14, v127, v12
	s_waitcnt lgkmcnt(2)
	v_pk_add_f32 v[16:17], v[18:19], v[28:29]
	s_waitcnt lgkmcnt(1)
	v_add_f32_e32 v10, v10, v22
	ds_bpermute_b32 v15, v127, v13
	ds_bpermute_b32 v18, v127, v16
	ds_bpermute_b32 v19, v127, v17
	ds_bpermute_b32 v22, v127, v10
	s_and_saveexec_b64 s[8:9], s[6:7]
	s_cbranch_execz .LBB0_843
	s_add_i32 s1, s14, 0
	s_waitcnt lgkmcnt(1)
	v_pk_add_f32 v[16:17], v[16:17], v[18:19]
	v_pk_add_f32 v[14:15], v[12:13], v[14:15]
	v_lshl_add_u32 v12, v24, 2, s1
	v_cmp_eq_u32_e32 vcc, 0, v121
	ds_write_b128 v12, v[14:17] offset:2176
	s_and_b64 exec, exec, vcc
	s_cbranch_execz .LBB0_843
	s_waitcnt lgkmcnt(1)
	v_add_f32_e32 v10, v10, v22
	v_mov_b32_e32 v12, s1
	ds_write_b32 v12, v10 offset:2432

; #define LAS __attribute__((address_space(3)))
; __global__ void __launch_bounds__(NWAVES * 64, 2) hymba_fwd(Args args) {
;     extern __shared__ __attribute__((aligned(16))) unsigned char lds[];
;     Frame F;
;     F.lds = (LAS unsigned char*)lds; F.MISC = (volatile LAS unsigned*)(F.lds + MISC_OFF);
;     F.tid = threadIdx.x; F.lane = F.tid & 63; F.wave = __builtin_amdgcn_readfirstlane(F.tid >> 6); F.G = gridDim.x;
;     F.item_mask = args.item_mask; F.ws = args.ws; F.ctl = (gu32*)(args.ws + WS_CTL); F.out = args.out;
;     for (int u = F.tid; u < (LDS_BYTES - LDSCTL_OFF) / 4; u += NWAVES * 64) ((LAS unsigned*)(F.lds + LDSCTL_OFF))[u] = 0u;
;     __syncthreads();
;     const int lo = args.ph_lo, hi = args.ph_hi;
;     XcdBarrier bar; bar.bar = (unsigned*)(F.ctl + CW_BAR); bar.x = 0; bar.st = nullptr;
;     if (hi - lo > 1) bar = xcd_barrier_post((unsigned*)(F.ctl + CW_BAR), F.MISC + 8);
	.amdhsa_kernel _Z9hymba_fwd4Args
		.amdhsa_group_segment_fixed_size 0
		.amdhsa_private_segment_fixed_size 0
		.amdhsa_kernarg_size 392
		.amdhsa_user_sgpr_count 2
		.amdhsa_user_sgpr_dispatch_ptr 0
		.amdhsa_user_sgpr_queue_ptr 0
		.amdhsa_user_sgpr_kernarg_segment_ptr 1
		.amdhsa_user_sgpr_dispatch_id 0
		.amdhsa_user_sgpr_kernarg_preload_length 0
		.amdhsa_user_sgpr_kernarg_preload_offset 0
		.amdhsa_user_sgpr_private_segment_size 0
		.amdhsa_uses_dynamic_stack 0
		.amdhsa_enable_private_segment 0
		.amdhsa_system_sgpr_workgroup_id_x 1
		.amdhsa_system_sgpr_workgroup_id_y 0
		.amdhsa_system_sgpr_workgroup_id_z 0
		.amdhsa_system_sgpr_workgroup_info 0
		.amdhsa_system_vgpr_workitem_id 0
		.amdhsa_next_free_vgpr 247
		.amdhsa_next_free_sgpr 100
		.amdhsa_accum_offset 248
		.amdhsa_reserve_vcc 1
		.amdhsa_float_round_mode_32 0
		.amdhsa_float_round_mode_16_64 0
		.amdhsa_float_denorm_mode_32 3
		.amdhsa_float_denorm_mode_16_64 3
		.amdhsa_dx10_clamp 1
		.amdhsa_ieee_mode 1
		.amdhsa_fp16_overflow 0
		.amdhsa_tg_split 0
		.amdhsa_exception_fp_ieee_invalid_op 0
		.amdhsa_exception_fp_denorm_src 0
		.amdhsa_exception_fp_ieee_div_zero 0
		.amdhsa_exception_fp_ieee_overflow 0
		.amdhsa_exception_fp_ieee_underflow 0
		.amdhsa_exception_fp_ieee_inexact 0
		.amdhsa_exception_int_div_zero 0
	.end_amdhsa_kernel

; __global__ void __launch_bounds__(NWAVES * 64, 2) hymba_fwd(Args args) {
;     extern __shared__ __attribute__((aligned(16))) unsigned char lds[];
amdhsa.kernels:
  - .agpr_count:     0
    .args:
      - .offset:         0
        .size:           136
        .value_kind:     by_value
      - .offset:         136
        .size:           4
        .value_kind:     hidden_block_count_x
      - .offset:         140
        .size:           4
        .value_kind:     hidden_block_count_y
      - .offset:         144
        .size:           4
        .value_kind:     hidden_block_count_z
      - .offset:         148
        .size:           2
        .value_kind:     hidden_group_size_x
      - .offset:         150
        .size:           2
        .value_kind:     hidden_group_size_y
      - .offset:         152
        .size:           2
        .value_kind:     hidden_group_size_z
      - .offset:         154
        .size:           2
        .value_kind:     hidden_remainder_x
      - .offset:         156
        .size:           2
        .value_kind:     hidden_remainder_y
      - .offset:         158
        .size:           2
        .value_kind:     hidden_remainder_z
      - .offset:         176
        .size:           8
        .value_kind:     hidden_global_offset_x
      - .offset:         184
        .size:           8
        .value_kind:     hidden_global_offset_y
      - .offset:         192
        .size:           8
        .value_kind:     hidden_global_offset_z
      - .offset:         200
        .size:           2
        .value_kind:     hidden_grid_dims
      - .offset:         256
        .size:           4
        .value_kind:     hidden_dynamic_lds_size
    .group_segment_fixed_size: 0
    .kernarg_segment_align: 8
    .kernarg_segment_size: 392
    .language:       OpenCL C
    .language_version:
      - 2
      - 0
    .max_flat_workgroup_size: 512
    .name:           _Z9hymba_fwd4Args
    .private_segment_fixed_size: 0
    .sgpr_count:     106
    .sgpr_spill_count: 112
    .symbol:         _Z9hymba_fwd4Args.kd
    .uniform_work_group_size: 1
    .uses_dynamic_stack: false
    .vgpr_count:     247
    .vgpr_spill_count: 0
    .wavefront_size: 64
